# K-loop restructured to two 32-MFMA phases per K-tile (8 barriers per iteration): reads+stages, drain, barrier, 32 MFMA, barrier; GEMM prologue waits for the whole first K-tile before its first barrier
# speedup vs baseline: 1.0115x; 1.0086x over previous
; __device__ __forceinline__ int opaque_tid() { int t = threadIdx.x; asm volatile("" : "+v"(t)); return t; }
; #define PG8_STAGE(bufoff, gbase, voff) do { _Pragma("unroll") for (int _i = 0; _i < 2; ++_i) \
;         __builtin_amdgcn_global_load_lds((const unsigned*)((const char*)(gbase) + (voff)[_i]), (LAS unsigned*)(lds + (bufoff) + ldsw + _i * 8192), 16, 0, 0); } while (0)
; #define PG8_WAIT_V(n) asm volatile("s_waitcnt vmcnt(" #n ")" ::: "memory")
; #define PG8_BAR __builtin_amdgcn_s_barrier()
; template <class Epi>
; __device__ __forceinline__ void gemm_phase(LAS unsigned char* lds, const Gemm g, const StaticOrder& S, const Epi& E) {
;     const int tid = opaque_tid(), wid = __builtin_amdgcn_readfirstlane(tid >> 6), lane = tid & 63, wr = wid >> 2, wc = wid & 3, fr = lane & 15, fq = lane >> 4;
;     const int K = g.K, nt = K / BK;
;     unsigned voffA[2], voffB[2];
; #pragma unroll
;     for (int i = 0; i < 2; ++i) { voffA[i] = (unsigned)(tid * 16 + i * 8192); voffB[i] = voffA[i]; }
;     const size_t kstep = (size_t)HTB;
;     const size_t hstepA = (size_t)nt * HTB, hstepB = hstepA;
;     const size_t tstepA = 2 * hstepA, tstepB = tstepA;
;     const unsigned ldsw = (unsigned)wid * 1024u;
;     const int aoff = lds_byte(wr * 64 + fr, fq * 8), boff = lds_byte(wc * 32 + fr, fq * 8);
;     ...
;     const char* cA = (const char*)g.A + (size_t)cur.pm * tstepA; const char* cB = (const char*)g.Bt + (size_t)cur.pn * tstepB;
;     PG8_STAGE(PG8_SB(0, 0), cB, voffB); PG8_STAGE(PG8_SA(0, 0), cA, voffA); PG8_STAGE(PG8_SB(0, 1), cB + hstepB, voffB); PG8_STAGE(PG8_SA(0, 1), cA + hstepA, voffA);
;     if (wr == 1) PG8_BAR;
;     PG8_WAIT_V(4); PG8_BAR;
;     PG8_STAGE(PG8_SB(1, 0), cB + kstep, voffB); PG8_STAGE(PG8_SA(1, 0), cA + kstep, voffA); PG8_STAGE(PG8_SB(1, 1), cB + hstepB + kstep, voffB);
;     PG8_WAIT_V(6); PG8_BAR;
.LBB0_133:
	s_and_b32 s4, s4, 3
	s_lshl_b32 s41, s1, 6
	s_lshl_b32 s14, s1, 13
	s_lshl_b32 s42, s4, 5
	s_lshl_b32 s15, s4, 12
	s_add_u32 s4, s24, 0x4000
	v_mov_b32_e32 v129, v153
	s_addc_u32 s5, s25, 0
	s_add_i32 m0, s37, 0x18000
	v_lshl_add_u64 v[2:3], s[4:5], 0, v[128:129]
	v_mov_b32_e32 v131, v153
	s_waitcnt vmcnt(0)
	s_barrier
	global_load_lds_dwordx4 v[2:3], off
	s_add_i32 m0, s37, 0x1a000
	v_lshl_add_u64 v[2:3], s[4:5], 0, v[130:131]
	s_add_u32 s4, s22, 0x4000
	s_addc_u32 s5, s23, 0
	s_add_i32 s43, s37, 0x8000
	global_load_lds_dwordx4 v[2:3], off
	v_lshl_add_u64 v[2:3], s[4:5], 0, v[128:129]
	s_mov_b32 m0, s43
	s_add_i32 s44, s37, 0xa000
	global_load_lds_dwordx4 v[2:3], off
	v_lshl_add_u64 v[2:3], s[4:5], 0, v[130:131]
	s_add_u32 s4, s24, 0x84000
	s_mov_b32 m0, s44
	s_addc_u32 s5, s25, 0
	global_load_lds_dwordx4 v[2:3], off
	s_add_i32 m0, s37, 0x1c000
	v_lshl_add_u64 v[2:3], s[4:5], 0, v[128:129]
	global_load_lds_dwordx4 v[2:3], off
	v_lshl_add_u64 v[2:3], s[4:5], 0, v[130:131]
	s_add_i32 m0, s37, 0x1e000
	s_sext_i32_i8 s21, s0
	global_load_lds_dwordx4 v[2:3], off
	s_lshl_b32 s0, s1, 3
	s_bfe_u32 s45, s31, 0x10006
	s_and_b32 s0, s0, 8
	s_or_b32 s0, s0, s45
	s_waitcnt vmcnt(6)
	s_barrier
	s_lshl_b32 s46, s0, 10
	s_load_dword s0, s[84:85], 0x0
	v_and_b32_e32 v132, 15, v0
	v_and_b32_e32 v133, 48, v0
	v_lshlrev_b32_e32 v0, 2, v0
	v_lshl_or_b32 v1, v132, 6, v133
	v_and_b32_e32 v0, 32, v0
	v_bitop3_b32 v2, v1, s14, v0 bitop3:0xde
	v_bitop3_b32 v134, v1, s15, v0 bitop3:0xde
	s_waitcnt lgkmcnt(0)
	s_ashr_i32 s47, s0, 31
	s_mov_b32 s48, 0
	v_add_u32_e32 v135, 0, v2

; #define PG8_STAGE(bufoff, gbase, voff) do { _Pragma("unroll") for (int _i = 0; _i < 2; ++_i) \
;         __builtin_amdgcn_global_load_lds((const unsigned*)((const char*)(gbase) + (voff)[_i]), (LAS unsigned*)(lds + (bufoff) + ldsw + _i * 8192), 16, 0, 0); } while (0)
; #define PG8_LDA(dst, b, h) do { _Pragma("unroll") for (int m = 0; m < 4; ++m) _Pragma("unroll") for (int k = 0; k < 2; ++k) dst[m][k] = *(const LAS bf16x8*)(lds + PG8_SA(b, h) + aoff + m * 2048 + k * 1024); } while (0)
; #define PG8_LDB(dst, b, h) do { _Pragma("unroll") for (int n = 0; n < 2; ++n) _Pragma("unroll") for (int k = 0; k < 2; ++k) dst[n][k] = *(const LAS bf16x8*)(lds + PG8_SB(b, h) + boff + n * 2048 + k * 1024); } while (0)
; #define PG8_WAIT_V(n) asm volatile("s_waitcnt vmcnt(" #n ")" ::: "memory")
; #define PG8_WAIT_L(n) asm volatile("s_waitcnt lgkmcnt(" #n ")" ::: "memory")
; #define PG8_BAR __builtin_amdgcn_s_barrier()
; #define PG8_SCHED __builtin_amdgcn_sched_barrier(0)
; template <class Epi>
; __device__ __forceinline__ void gemm_phase(LAS unsigned char* lds, const Gemm g, const StaticOrder& S, const Epi& E) {
;     ...
;         const bool has_next = S.next(ui + 1, nxt);
;         const char* nA = has_next ? (const char*)g.A + (size_t)nxt.pm * tstepA : cA; const char* nB = has_next ? (const char*)g.Bt + (size_t)nxt.pn * tstepB : cB;
;         for (int t = 0; t < nt; t += 2) {
;             const bool last = (t == nt - 2);
;             const char* a1 = cA + (size_t)(t + 1) * kstep;
;             const char* a2 = last ? nA : cA + (size_t)(t + 2) * kstep; const char* b2 = last ? nB : cB + (size_t)(t + 2) * kstep;
;             const char* a3 = a2 + kstep; const char* b3 = b2 + kstep;
;             PG8_LDB(B0, 0, 0); PG8_SCHED; PG8_LDA(At, 0, 0); PG8_STAGE(PG8_SA(1, 1), a1 + hstepA, voffA);
;             PG8_WAIT_L(8); PG8_BAR; PG8_WAIT_L(0); PG8_MMA(0, 0, At, B0); PG8_BAR; PG8_SCHED;
;             PG8_LDB(B1, 0, 1); PG8_STAGE(PG8_SB(0, 0), b2, voffB);
;             PG8_BAR; PG8_WAIT_L(0); PG8_MMA(0, 1, At, B1); PG8_BAR;
;             PG8_LDA(At, 0, 1); PG8_STAGE(PG8_SA(0, 0), a2, voffA);
;             PG8_BAR; PG8_WAIT_L(0); PG8_MMA(1, 0, At, B0); PG8_BAR; PG8_SCHED;
;             PG8_STAGE(PG8_SB(0, 1), b2 + hstepB, voffB);
;             PG8_WAIT_V(6); PG8_BAR; PG8_MMA(1, 1, At, B1); PG8_BAR;
.LBB0_140:
	v_mov_b64_e32 v[0:1], 0x800
	s_ashr_i32 s15, s14, 31
	v_cmp_lt_i64_e32 vcc, s[16:17], v[0:1]
	s_lshl_b64 s[16:17], s[14:15], 20
	v_readlane_b32 s18, v252, 53
	v_readlane_b32 s19, v252, 54
	s_add_u32 s16, s18, s16
	s_addc_u32 s17, s19, s17
	s_and_b64 s[18:19], vcc, exec
	s_cselect_b32 s15, s17, s23
	s_cselect_b32 s49, s16, s22
	s_ashr_i32 s5, s4, 31
	s_lshl_b64 s[18:19], s[4:5], 20
	s_add_u32 s18, s34, s18
	s_addc_u32 s19, s35, s19
	s_and_b64 s[26:27], vcc, exec
	s_cselect_b32 s5, s19, s25
	s_cselect_b32 s50, s18, s24
	s_add_u32 s22, s22, 0x84000
	s_addc_u32 s23, s23, 0
	s_add_u32 s51, s24, 0x8000
	s_addc_u32 s52, s25, 0
	s_mov_b32 s54, -2
	s_add_u32 s24, s22, 0xfff84000
	s_addc_u32 s25, s23, -1
	s_cmp_eq_u32 s54, 28
	s_cselect_b32 s28, s49, s24
	s_cselect_b32 s29, s15, s25
	s_cselect_b32 s24, s50, s51
	s_cselect_b32 s25, s5, s52
	s_add_u32 s26, s28, 0x4000
	s_addc_u32 s27, s29, 0
	s_add_i32 s55, 0, 0x10000
	v_add_u32_e32 v148, s55, v134
	ds_read_b128 v[136:139], v148
	ds_read_b128 v[144:147], v148 offset:2048
	ds_read_b128 v[140:143], v148 offset:1024
	ds_read_b128 v[148:151], v148 offset:3072
	v_lshl_add_u64 v[188:189], s[22:23], 0, v[128:129]
	s_add_i32 m0, s37, 0xc000
	ds_read_b128 v[156:159], v135
	ds_read_b128 v[164:167], v135 offset:2048
	ds_read_b128 v[172:175], v135 offset:4096
	ds_read_b128 v[180:183], v135 offset:6144
	ds_read_b128 v[160:163], v135 offset:1024
	ds_read_b128 v[168:171], v135 offset:3072
	ds_read_b128 v[176:179], v135 offset:5120
	ds_read_b128 v[184:187], v135 offset:7168
	global_load_lds_dwordx4 v[188:189], off
	s_add_i32 m0, s37, 0xe000
	v_lshl_add_u64 v[188:189], s[22:23], 0, v[130:131]
	global_load_lds_dwordx4 v[188:189], off
	s_add_i32 s58, 0, 0x14000
	s_add_i32 s55, s55, s36
	v_add_u32_e32 v152, s58, v134
	ds_read_b128 v[188:191], v152
	ds_read_b128 v[196:199], v152 offset:2048
	ds_read_b128 v[192:195], v152 offset:1024
	ds_read_b128 v[200:203], v152 offset:3072
	s_waitcnt lgkmcnt(0)
	s_barrier
	v_mfma_f32_16x16x32_bf16 v[124:127], v[136:139], v[156:159], 0
	s_setprio 1
	v_mfma_f32_16x16x32_bf16 v[120:123], v[144:147], v[156:159], 0
	v_mfma_f32_16x16x32_bf16 v[108:111], v[136:139], v[164:167], 0
	v_mfma_f32_16x16x32_bf16 v[104:107], v[144:147], v[164:167], 0
	v_mfma_f32_16x16x32_bf16 v[92:95], v[136:139], v[172:175], 0
	v_mfma_f32_16x16x32_bf16 v[88:91], v[144:147], v[172:175], 0
	v_mfma_f32_16x16x32_bf16 v[76:79], v[136:139], v[180:183], 0
	v_mfma_f32_16x16x32_bf16 v[72:75], v[144:147], v[180:183], 0
	v_mfma_f32_16x16x32_bf16 v[124:127], v[140:143], v[160:163], v[124:127]
	v_mfma_f32_16x16x32_bf16 v[120:123], v[148:151], v[160:163], v[120:123]
	v_mfma_f32_16x16x32_bf16 v[108:111], v[140:143], v[168:171], v[108:111]
	v_mfma_f32_16x16x32_bf16 v[104:107], v[148:151], v[168:171], v[104:107]
	v_mfma_f32_16x16x32_bf16 v[92:95], v[140:143], v[176:179], v[92:95]
	v_mfma_f32_16x16x32_bf16 v[88:91], v[148:151], v[176:179], v[88:91]
	v_mfma_f32_16x16x32_bf16 v[76:79], v[140:143], v[184:187], v[76:79]
	v_mfma_f32_16x16x32_bf16 v[72:75], v[148:151], v[184:187], v[72:75]
	v_mfma_f32_16x16x32_bf16 v[116:119], v[188:191], v[156:159], 0
	v_mfma_f32_16x16x32_bf16 v[112:115], v[196:199], v[156:159], 0
	v_mfma_f32_16x16x32_bf16 v[100:103], v[188:191], v[164:167], 0
	v_mfma_f32_16x16x32_bf16 v[96:99], v[196:199], v[164:167], 0
	v_mfma_f32_16x16x32_bf16 v[84:87], v[188:191], v[172:175], 0
	v_mfma_f32_16x16x32_bf16 v[80:83], v[196:199], v[172:175], 0
	v_mfma_f32_16x16x32_bf16 v[68:71], v[188:191], v[180:183], 0
	v_mfma_f32_16x16x32_bf16 v[64:67], v[196:199], v[180:183], 0
	v_mfma_f32_16x16x32_bf16 v[116:119], v[192:195], v[160:163], v[116:119]
	v_mfma_f32_16x16x32_bf16 v[112:115], v[200:203], v[160:163], v[112:115]
	v_mfma_f32_16x16x32_bf16 v[100:103], v[192:195], v[168:171], v[100:103]
	v_mfma_f32_16x16x32_bf16 v[96:99], v[200:203], v[168:171], v[96:99]
	v_mfma_f32_16x16x32_bf16 v[84:87], v[192:195], v[176:179], v[84:87]
	v_mfma_f32_16x16x32_bf16 v[80:83], v[200:203], v[176:179], v[80:83]
	v_mfma_f32_16x16x32_bf16 v[68:71], v[192:195], v[184:187], v[68:71]
	s_setprio 0
	v_mfma_f32_16x16x32_bf16 v[64:67], v[200:203], v[184:187], v[64:67]
	s_barrier
	ds_read_b128 v[156:159], v135 offset:16384
	ds_read_b128 v[164:167], v135 offset:18432
	ds_read_b128 v[172:175], v135 offset:20480
	ds_read_b128 v[180:183], v135 offset:22528
	ds_read_b128 v[160:163], v135 offset:17408
	ds_read_b128 v[168:171], v135 offset:19456
	ds_read_b128 v[176:179], v135 offset:21504
	ds_read_b128 v[184:187], v135 offset:23552
	s_mov_b32 m0, s55
	v_lshl_add_u64 v[204:205], s[24:25], 0, v[128:129]
	global_load_lds_dwordx4 v[204:205], off
	s_add_i32 m0, s55, 0x2000
	v_lshl_add_u64 v[204:205], s[24:25], 0, v[130:131]
	global_load_lds_dwordx4 v[204:205], off
	s_mov_b32 m0, s37
	v_lshl_add_u64 v[204:205], s[28:29], 0, v[128:129]
	global_load_lds_dwordx4 v[204:205], off
	s_mov_b32 m0, s38
	v_lshl_add_u64 v[204:205], s[28:29], 0, v[130:131]
	global_load_lds_dwordx4 v[204:205], off
	s_add_u32 s56, s24, 0x80000
	s_addc_u32 s57, s25, 0
	s_add_i32 s55, s58, s36
	s_mov_b32 m0, s55
	v_lshl_add_u64 v[204:205], s[56:57], 0, v[128:129]
	global_load_lds_dwordx4 v[204:205], off
	s_add_i32 m0, s55, 0x2000
	v_lshl_add_u64 v[204:205], s[56:57], 0, v[130:131]
	global_load_lds_dwordx4 v[204:205], off
	s_waitcnt vmcnt(6)
	s_waitcnt lgkmcnt(0)
	s_barrier
; #define PG8_STAGE(bufoff, gbase, voff) do { _Pragma("unroll") for (int _i = 0; _i < 2; ++_i) \
;         __builtin_amdgcn_global_load_lds((const unsigned*)((const char*)(gbase) + (voff)[_i]), (LAS unsigned*)(lds + (bufoff) + ldsw + _i * 8192), 16, 0, 0); } while (0)
; #define PG8_LDA(dst, b, h) do { _Pragma("unroll") for (int m = 0; m < 4; ++m) _Pragma("unroll") for (int k = 0; k < 2; ++k) dst[m][k] = *(const LAS bf16x8*)(lds + PG8_SA(b, h) + aoff + m * 2048 + k * 1024); } while (0)
; #define PG8_LDB(dst, b, h) do { _Pragma("unroll") for (int n = 0; n < 2; ++n) _Pragma("unroll") for (int k = 0; k < 2; ++k) dst[n][k] = *(const LAS bf16x8*)(lds + PG8_SB(b, h) + boff + n * 2048 + k * 1024); } while (0)
; #define PG8_MMA(ai, bj, At, Bt) do { __builtin_amdgcn_s_setprio(1); _Pragma("unroll") for (int m = 0; m < 4; ++m) _Pragma("unroll") for (int n = 0; n < 2; ++n) _Pragma("unroll") for (int k = 0; k < 2; ++k) \
;         acc[ai][bj][m][n] = __builtin_amdgcn_mfma_f32_16x16x32_bf16(Bt[n][k], At[m][k], acc[ai][bj][m][n], 0, 0, 0); __builtin_amdgcn_s_setprio(0); } while (0)
; #define PG8_WAIT_V(n) asm volatile("s_waitcnt vmcnt(" #n ")" ::: "memory")
; #define PG8_WAIT_L(n) asm volatile("s_waitcnt lgkmcnt(" #n ")" ::: "memory")
; #define PG8_BAR __builtin_amdgcn_s_barrier()
; #define PG8_SCHED __builtin_amdgcn_sched_barrier(0)
; template <class Epi>
; __device__ __forceinline__ void gemm_phase(LAS unsigned char* lds, const Gemm g, const StaticOrder& S, const Epi& E) {
;     ...
;             PG8_BAR; PG8_WAIT_L(0); PG8_MMA(1, 0, At, B0); PG8_BAR; PG8_SCHED;
;             PG8_STAGE(PG8_SB(0, 1), b2 + hstepB, voffB);
;             PG8_WAIT_V(6); PG8_BAR; PG8_MMA(1, 1, At, B1); PG8_BAR;
;             PG8_LDB(B0, 1, 0); PG8_SCHED; PG8_LDA(At, 1, 0); PG8_STAGE(PG8_SA(0, 1), a2 + hstepA, voffA);
;             PG8_WAIT_L(8); PG8_BAR; PG8_WAIT_L(0); PG8_MMA(0, 0, At, B0); PG8_BAR; PG8_SCHED;
;             PG8_LDB(B1, 1, 1); PG8_STAGE(PG8_SB(1, 0), b3, voffB);
;             PG8_BAR; PG8_WAIT_L(0); PG8_MMA(0, 1, At, B1); PG8_BAR;
	v_mfma_f32_16x16x32_bf16 v[60:63], v[136:139], v[156:159], 0
	s_setprio 1
	v_mfma_f32_16x16x32_bf16 v[56:59], v[144:147], v[156:159], 0
	v_mfma_f32_16x16x32_bf16 v[44:47], v[136:139], v[164:167], 0
	v_mfma_f32_16x16x32_bf16 v[40:43], v[144:147], v[164:167], 0
	v_mfma_f32_16x16x32_bf16 v[28:31], v[136:139], v[172:175], 0
	v_mfma_f32_16x16x32_bf16 v[24:27], v[144:147], v[172:175], 0
	v_mfma_f32_16x16x32_bf16 v[12:15], v[136:139], v[180:183], 0
	v_mfma_f32_16x16x32_bf16 v[8:11], v[144:147], v[180:183], 0
	v_mfma_f32_16x16x32_bf16 v[60:63], v[140:143], v[160:163], v[60:63]
	v_mfma_f32_16x16x32_bf16 v[56:59], v[148:151], v[160:163], v[56:59]
	v_mfma_f32_16x16x32_bf16 v[44:47], v[140:143], v[168:171], v[44:47]
	v_mfma_f32_16x16x32_bf16 v[40:43], v[148:151], v[168:171], v[40:43]
	v_mfma_f32_16x16x32_bf16 v[28:31], v[140:143], v[176:179], v[28:31]
	v_mfma_f32_16x16x32_bf16 v[24:27], v[148:151], v[176:179], v[24:27]
	v_mfma_f32_16x16x32_bf16 v[12:15], v[140:143], v[184:187], v[12:15]
	v_mfma_f32_16x16x32_bf16 v[8:11], v[148:151], v[184:187], v[8:11]
	v_mfma_f32_16x16x32_bf16 v[52:55], v[188:191], v[156:159], 0
	v_mfma_f32_16x16x32_bf16 v[48:51], v[196:199], v[156:159], 0
	s_add_i32 s55, 0, 0x18000
	v_add_u32_e32 v148, s55, v134
	v_mfma_f32_16x16x32_bf16 v[36:39], v[188:191], v[164:167], 0
	v_mfma_f32_16x16x32_bf16 v[32:35], v[196:199], v[164:167], 0
	v_mfma_f32_16x16x32_bf16 v[20:23], v[188:191], v[172:175], 0
	v_mfma_f32_16x16x32_bf16 v[16:19], v[196:199], v[172:175], 0
	v_mfma_f32_16x16x32_bf16 v[4:7], v[188:191], v[180:183], 0
	v_mfma_f32_16x16x32_bf16 v[0:3], v[196:199], v[180:183], 0
	v_mfma_f32_16x16x32_bf16 v[52:55], v[192:195], v[160:163], v[52:55]
	v_mfma_f32_16x16x32_bf16 v[48:51], v[200:203], v[160:163], v[48:51]
	v_mfma_f32_16x16x32_bf16 v[36:39], v[192:195], v[168:171], v[36:39]
	v_mfma_f32_16x16x32_bf16 v[32:35], v[200:203], v[168:171], v[32:35]
	v_mfma_f32_16x16x32_bf16 v[20:23], v[192:195], v[176:179], v[20:23]
	v_mfma_f32_16x16x32_bf16 v[16:19], v[200:203], v[176:179], v[16:19]
	v_mfma_f32_16x16x32_bf16 v[4:7], v[192:195], v[184:187], v[4:7]
	s_setprio 0
	v_mfma_f32_16x16x32_bf16 v[0:3], v[200:203], v[184:187], v[0:3]
	s_barrier
	ds_read_b128 v[136:139], v148
	ds_read_b128 v[144:147], v148 offset:2048
	ds_read_b128 v[140:143], v148 offset:1024
	ds_read_b128 v[148:151], v148 offset:3072
	s_add_u32 s28, s28, 0x80000
	s_addc_u32 s29, s29, 0
	s_mov_b32 m0, s39
	v_lshl_add_u64 v[188:189], s[28:29], 0, v[128:129]
	ds_read_b128 v[156:159], v135 offset:32768
	ds_read_b128 v[164:167], v135 offset:34816
	ds_read_b128 v[172:175], v135 offset:36864
	ds_read_b128 v[180:183], v135 offset:38912
	ds_read_b128 v[160:163], v135 offset:33792
	ds_read_b128 v[168:171], v135 offset:35840
	ds_read_b128 v[176:179], v135 offset:37888
	ds_read_b128 v[184:187], v135 offset:39936
	global_load_lds_dwordx4 v[188:189], off
	s_mov_b32 m0, s40
	v_lshl_add_u64 v[188:189], s[28:29], 0, v[130:131]
	global_load_lds_dwordx4 v[188:189], off
	s_add_i32 s56, 0, 0x1c000
	s_add_u32 s28, s24, 0x4000
	s_addc_u32 s29, s25, 0
	s_add_i32 s55, s55, s36
	v_add_u32_e32 v152, s56, v134
	ds_read_b128 v[188:191], v152
	ds_read_b128 v[196:199], v152 offset:2048
	ds_read_b128 v[192:195], v152 offset:1024
	ds_read_b128 v[200:203], v152 offset:3072
	s_waitcnt lgkmcnt(0)
	s_barrier
	v_mfma_f32_16x16x32_bf16 v[124:127], v[136:139], v[156:159], v[124:127]
	s_setprio 1
	v_mfma_f32_16x16x32_bf16 v[120:123], v[144:147], v[156:159], v[120:123]
	v_mfma_f32_16x16x32_bf16 v[108:111], v[136:139], v[164:167], v[108:111]
	v_mfma_f32_16x16x32_bf16 v[104:107], v[144:147], v[164:167], v[104:107]
	v_mfma_f32_16x16x32_bf16 v[92:95], v[136:139], v[172:175], v[92:95]
	v_mfma_f32_16x16x32_bf16 v[88:91], v[144:147], v[172:175], v[88:91]
	v_mfma_f32_16x16x32_bf16 v[76:79], v[136:139], v[180:183], v[76:79]
	v_mfma_f32_16x16x32_bf16 v[72:75], v[144:147], v[180:183], v[72:75]
	v_mfma_f32_16x16x32_bf16 v[124:127], v[140:143], v[160:163], v[124:127]
	v_mfma_f32_16x16x32_bf16 v[120:123], v[148:151], v[160:163], v[120:123]
	v_mfma_f32_16x16x32_bf16 v[108:111], v[140:143], v[168:171], v[108:111]
	v_mfma_f32_16x16x32_bf16 v[104:107], v[148:151], v[168:171], v[104:107]
	v_mfma_f32_16x16x32_bf16 v[92:95], v[140:143], v[176:179], v[92:95]
	v_mfma_f32_16x16x32_bf16 v[88:91], v[148:151], v[176:179], v[88:91]
	v_mfma_f32_16x16x32_bf16 v[76:79], v[140:143], v[184:187], v[76:79]
	v_mfma_f32_16x16x32_bf16 v[72:75], v[148:151], v[184:187], v[72:75]
	v_mfma_f32_16x16x32_bf16 v[116:119], v[188:191], v[156:159], v[116:119]
	v_mfma_f32_16x16x32_bf16 v[112:115], v[196:199], v[156:159], v[112:115]
	v_mfma_f32_16x16x32_bf16 v[100:103], v[188:191], v[164:167], v[100:103]
	v_mfma_f32_16x16x32_bf16 v[96:99], v[196:199], v[164:167], v[96:99]
	v_mfma_f32_16x16x32_bf16 v[84:87], v[188:191], v[172:175], v[84:87]
	v_mfma_f32_16x16x32_bf16 v[80:83], v[196:199], v[172:175], v[80:83]
	v_mfma_f32_16x16x32_bf16 v[68:71], v[188:191], v[180:183], v[68:71]
	v_mfma_f32_16x16x32_bf16 v[64:67], v[196:199], v[180:183], v[64:67]
	v_mfma_f32_16x16x32_bf16 v[116:119], v[192:195], v[160:163], v[116:119]
	v_mfma_f32_16x16x32_bf16 v[112:115], v[200:203], v[160:163], v[112:115]
	v_mfma_f32_16x16x32_bf16 v[100:103], v[192:195], v[168:171], v[100:103]
	v_mfma_f32_16x16x32_bf16 v[96:99], v[200:203], v[168:171], v[96:99]
	v_mfma_f32_16x16x32_bf16 v[84:87], v[192:195], v[176:179], v[84:87]
	v_mfma_f32_16x16x32_bf16 v[80:83], v[200:203], v[176:179], v[80:83]
	v_mfma_f32_16x16x32_bf16 v[68:71], v[192:195], v[184:187], v[68:71]
	s_setprio 0
	v_mfma_f32_16x16x32_bf16 v[64:67], v[200:203], v[184:187], v[64:67]
	s_barrier
; #define PG8_STAGE(bufoff, gbase, voff) do { _Pragma("unroll") for (int _i = 0; _i < 2; ++_i) \
;         __builtin_amdgcn_global_load_lds((const unsigned*)((const char*)(gbase) + (voff)[_i]), (LAS unsigned*)(lds + (bufoff) + ldsw + _i * 8192), 16, 0, 0); } while (0)
; #define PG8_LDA(dst, b, h) do { _Pragma("unroll") for (int m = 0; m < 4; ++m) _Pragma("unroll") for (int k = 0; k < 2; ++k) dst[m][k] = *(const LAS bf16x8*)(lds + PG8_SA(b, h) + aoff + m * 2048 + k * 1024); } while (0)
; #define PG8_WAIT_V(n) asm volatile("s_waitcnt vmcnt(" #n ")" ::: "memory")
; #define PG8_WAIT_L(n) asm volatile("s_waitcnt lgkmcnt(" #n ")" ::: "memory")
; #define PG8_BAR __builtin_amdgcn_s_barrier()
; template <class Epi>
; __device__ __forceinline__ void gemm_phase(LAS unsigned char* lds, const Gemm g, const StaticOrder& S, const Epi& E) {
;     ...
;             const bool last = (t == nt - 2);
;             const char* a1 = cA + (size_t)(t + 1) * kstep;
;             const char* a2 = last ? nA : cA + (size_t)(t + 2) * kstep; const char* b2 = last ? nB : cB + (size_t)(t + 2) * kstep;
;             const char* a3 = a2 + kstep; const char* b3 = b2 + kstep;
;             PG8_LDB(B0, 0, 0); PG8_SCHED; PG8_LDA(At, 0, 0); PG8_STAGE(PG8_SA(1, 1), a1 + hstepA, voffA);
;             PG8_WAIT_L(8); PG8_BAR; PG8_WAIT_L(0); PG8_MMA(0, 0, At, B0); PG8_BAR; PG8_SCHED;
;             PG8_LDB(B1, 0, 1); PG8_STAGE(PG8_SB(0, 0), b2, voffB);
;             PG8_BAR; PG8_WAIT_L(0); PG8_MMA(0, 1, At, B1); PG8_BAR;
;             PG8_LDA(At, 0, 1); PG8_STAGE(PG8_SA(0, 0), a2, voffA);
;             PG8_BAR; PG8_WAIT_L(0); PG8_MMA(1, 0, At, B0); PG8_BAR; PG8_SCHED;
;             PG8_STAGE(PG8_SB(0, 1), b2 + hstepB, voffB);
;             PG8_WAIT_V(6); PG8_BAR; PG8_MMA(1, 1, At, B1); PG8_BAR;
;             PG8_LDB(B0, 1, 0); PG8_SCHED; PG8_LDA(At, 1, 0); PG8_STAGE(PG8_SA(0, 1), a2 + hstepA, voffA);
;             PG8_WAIT_L(8); PG8_BAR; PG8_WAIT_L(0); PG8_MMA(0, 0, At, B0); PG8_BAR; PG8_SCHED;
;             PG8_LDB(B1, 1, 1); PG8_STAGE(PG8_SB(1, 0), b3, voffB);
;             PG8_BAR; PG8_WAIT_L(0); PG8_MMA(0, 1, At, B1); PG8_BAR;
;             PG8_LDA(At, 1, 1); PG8_STAGE(PG8_SA(1, 0), a3, voffA);
;             PG8_BAR; PG8_WAIT_L(0); PG8_MMA(1, 0, At, B0); PG8_BAR; PG8_SCHED;
;             PG8_STAGE(PG8_SB(1, 1), b3 + hstepB, voffB);
;             PG8_WAIT_V(6); PG8_BAR; PG8_MMA(1, 1, At, B1); PG8_BAR;
	ds_read_b128 v[156:159], v135 offset:49152
	ds_read_b128 v[164:167], v135 offset:51200
	ds_read_b128 v[172:175], v135 offset:53248
	ds_read_b128 v[180:183], v135 offset:55296
	ds_read_b128 v[160:163], v135 offset:50176
	ds_read_b128 v[168:171], v135 offset:52224
	ds_read_b128 v[176:179], v135 offset:54272
	ds_read_b128 v[184:187], v135 offset:56320
	s_mov_b32 m0, s55
	v_lshl_add_u64 v[204:205], s[28:29], 0, v[128:129]
	global_load_lds_dwordx4 v[204:205], off
	s_add_i32 m0, s55, 0x2000
	v_lshl_add_u64 v[204:205], s[28:29], 0, v[130:131]
	global_load_lds_dwordx4 v[204:205], off
	s_mov_b32 m0, s43
	v_lshl_add_u64 v[204:205], s[26:27], 0, v[128:129]
	global_load_lds_dwordx4 v[204:205], off
	s_mov_b32 m0, s44
	v_lshl_add_u64 v[204:205], s[26:27], 0, v[130:131]
	global_load_lds_dwordx4 v[204:205], off
	s_add_u32 s24, s24, 0x84000
	s_addc_u32 s25, s25, 0
	s_add_i32 s26, s56, s36
	s_mov_b32 m0, s26
	v_lshl_add_u64 v[204:205], s[24:25], 0, v[128:129]
	global_load_lds_dwordx4 v[204:205], off
	s_add_i32 m0, s26, 0x2000
	v_lshl_add_u64 v[204:205], s[24:25], 0, v[130:131]
	global_load_lds_dwordx4 v[204:205], off
	s_waitcnt vmcnt(6)
	s_waitcnt lgkmcnt(0)
	s_barrier
	v_mfma_f32_16x16x32_bf16 v[60:63], v[136:139], v[156:159], v[60:63]
	s_setprio 1
	v_mfma_f32_16x16x32_bf16 v[56:59], v[144:147], v[156:159], v[56:59]
	v_mfma_f32_16x16x32_bf16 v[44:47], v[136:139], v[164:167], v[44:47]
	v_mfma_f32_16x16x32_bf16 v[40:43], v[144:147], v[164:167], v[40:43]
	v_mfma_f32_16x16x32_bf16 v[28:31], v[136:139], v[172:175], v[28:31]
	v_mfma_f32_16x16x32_bf16 v[24:27], v[144:147], v[172:175], v[24:27]
	v_mfma_f32_16x16x32_bf16 v[12:15], v[136:139], v[180:183], v[12:15]
	v_mfma_f32_16x16x32_bf16 v[8:11], v[144:147], v[180:183], v[8:11]
	v_mfma_f32_16x16x32_bf16 v[60:63], v[140:143], v[160:163], v[60:63]
	v_mfma_f32_16x16x32_bf16 v[56:59], v[148:151], v[160:163], v[56:59]
	v_mfma_f32_16x16x32_bf16 v[44:47], v[140:143], v[168:171], v[44:47]
	v_mfma_f32_16x16x32_bf16 v[40:43], v[148:151], v[168:171], v[40:43]
	v_mfma_f32_16x16x32_bf16 v[28:31], v[140:143], v[176:179], v[28:31]
	v_mfma_f32_16x16x32_bf16 v[24:27], v[148:151], v[176:179], v[24:27]
	v_mfma_f32_16x16x32_bf16 v[12:15], v[140:143], v[184:187], v[12:15]
	v_mfma_f32_16x16x32_bf16 v[8:11], v[148:151], v[184:187], v[8:11]
	v_mfma_f32_16x16x32_bf16 v[52:55], v[188:191], v[156:159], v[52:55]
	v_mfma_f32_16x16x32_bf16 v[48:51], v[196:199], v[156:159], v[48:51]
	s_add_i32 s54, s54, 2
	s_add_u32 s22, s22, 0x8000
	s_addc_u32 s23, s23, 0
	s_add_u32 s51, s51, 0x8000
	s_addc_u32 s52, s52, 0
	v_mfma_f32_16x16x32_bf16 v[36:39], v[188:191], v[164:167], v[36:39]
	v_mfma_f32_16x16x32_bf16 v[32:35], v[196:199], v[164:167], v[32:35]
	v_mfma_f32_16x16x32_bf16 v[20:23], v[188:191], v[172:175], v[20:23]
	v_mfma_f32_16x16x32_bf16 v[16:19], v[196:199], v[172:175], v[16:19]
	v_mfma_f32_16x16x32_bf16 v[4:7], v[188:191], v[180:183], v[4:7]
	v_mfma_f32_16x16x32_bf16 v[0:3], v[196:199], v[180:183], v[0:3]
	v_mfma_f32_16x16x32_bf16 v[52:55], v[192:195], v[160:163], v[52:55]
	v_mfma_f32_16x16x32_bf16 v[48:51], v[200:203], v[160:163], v[48:51]
	v_mfma_f32_16x16x32_bf16 v[36:39], v[192:195], v[168:171], v[36:39]
	v_mfma_f32_16x16x32_bf16 v[32:35], v[200:203], v[168:171], v[32:35]
	v_mfma_f32_16x16x32_bf16 v[20:23], v[192:195], v[176:179], v[20:23]
	v_mfma_f32_16x16x32_bf16 v[16:19], v[200:203], v[176:179], v[16:19]
	v_mfma_f32_16x16x32_bf16 v[4:7], v[192:195], v[184:187], v[4:7]
	s_cmp_gt_u32 s54, 29
	s_setprio 0
	v_mfma_f32_16x16x32_bf16 v[0:3], v[200:203], v[184:187], v[0:3]
	s_barrier
	s_cbranch_scc0 .LBB0_141
	s_branch .Lpeel_done_141
.LBB0_141:
	s_add_u32 s24, s22, 0xfff84000
	s_addc_u32 s25, s23, -1
	s_cmp_eq_u32 s54, 28
	s_cselect_b32 s28, s49, s24
	s_cselect_b32 s29, s15, s25
	s_cselect_b32 s24, s50, s51
	s_cselect_b32 s25, s5, s52
	s_add_u32 s26, s28, 0x4000
	s_addc_u32 s27, s29, 0
	s_add_i32 s55, 0, 0x10000
	v_add_u32_e32 v148, s55, v134
	ds_read_b128 v[136:139], v148
	ds_read_b128 v[144:147], v148 offset:2048
	ds_read_b128 v[140:143], v148 offset:1024
	ds_read_b128 v[148:151], v148 offset:3072
	v_lshl_add_u64 v[188:189], s[22:23], 0, v[128:129]
	s_add_i32 m0, s37, 0xc000
	ds_read_b128 v[156:159], v135
	ds_read_b128 v[164:167], v135 offset:2048
	ds_read_b128 v[172:175], v135 offset:4096
	ds_read_b128 v[180:183], v135 offset:6144
	ds_read_b128 v[160:163], v135 offset:1024
	ds_read_b128 v[168:171], v135 offset:3072
	ds_read_b128 v[176:179], v135 offset:5120
	ds_read_b128 v[184:187], v135 offset:7168
	global_load_lds_dwordx4 v[188:189], off
	s_add_i32 m0, s37, 0xe000
	v_lshl_add_u64 v[188:189], s[22:23], 0, v[130:131]
	global_load_lds_dwordx4 v[188:189], off
	s_add_i32 s58, 0, 0x14000
	s_add_i32 s55, s55, s36
	v_add_u32_e32 v152, s58, v134
	ds_read_b128 v[188:191], v152
	ds_read_b128 v[196:199], v152 offset:2048
	ds_read_b128 v[192:195], v152 offset:1024
	ds_read_b128 v[200:203], v152 offset:3072
	s_waitcnt lgkmcnt(0)
	s_barrier
; #define PG8_STAGE(bufoff, gbase, voff) do { _Pragma("unroll") for (int _i = 0; _i < 2; ++_i) \
;         __builtin_amdgcn_global_load_lds((const unsigned*)((const char*)(gbase) + (voff)[_i]), (LAS unsigned*)(lds + (bufoff) + ldsw + _i * 8192), 16, 0, 0); } while (0)
; #define PG8_LDA(dst, b, h) do { _Pragma("unroll") for (int m = 0; m < 4; ++m) _Pragma("unroll") for (int k = 0; k < 2; ++k) dst[m][k] = *(const LAS bf16x8*)(lds + PG8_SA(b, h) + aoff + m * 2048 + k * 1024); } while (0)
; #define PG8_LDB(dst, b, h) do { _Pragma("unroll") for (int n = 0; n < 2; ++n) _Pragma("unroll") for (int k = 0; k < 2; ++k) dst[n][k] = *(const LAS bf16x8*)(lds + PG8_SB(b, h) + boff + n * 2048 + k * 1024); } while (0)
; #define PG8_MMA(ai, bj, At, Bt) do { __builtin_amdgcn_s_setprio(1); _Pragma("unroll") for (int m = 0; m < 4; ++m) _Pragma("unroll") for (int n = 0; n < 2; ++n) _Pragma("unroll") for (int k = 0; k < 2; ++k) \
;         acc[ai][bj][m][n] = __builtin_amdgcn_mfma_f32_16x16x32_bf16(Bt[n][k], At[m][k], acc[ai][bj][m][n], 0, 0, 0); __builtin_amdgcn_s_setprio(0); } while (0)
; #define PG8_WAIT_V(n) asm volatile("s_waitcnt vmcnt(" #n ")" ::: "memory")
; #define PG8_WAIT_L(n) asm volatile("s_waitcnt lgkmcnt(" #n ")" ::: "memory")
; #define PG8_BAR __builtin_amdgcn_s_barrier()
; #define PG8_SCHED __builtin_amdgcn_sched_barrier(0)
; template <class Epi>
; __device__ __forceinline__ void gemm_phase(LAS unsigned char* lds, const Gemm g, const StaticOrder& S, const Epi& E) {
;     ...
;             PG8_WAIT_L(8); PG8_BAR; PG8_WAIT_L(0); PG8_MMA(0, 0, At, B0); PG8_BAR; PG8_SCHED;
;             PG8_LDB(B1, 0, 1); PG8_STAGE(PG8_SB(0, 0), b2, voffB);
;             PG8_BAR; PG8_WAIT_L(0); PG8_MMA(0, 1, At, B1); PG8_BAR;
;             PG8_LDA(At, 0, 1); PG8_STAGE(PG8_SA(0, 0), a2, voffA);
;             PG8_BAR; PG8_WAIT_L(0); PG8_MMA(1, 0, At, B0); PG8_BAR; PG8_SCHED;
;             PG8_STAGE(PG8_SB(0, 1), b2 + hstepB, voffB);
;             PG8_WAIT_V(6); PG8_BAR; PG8_MMA(1, 1, At, B1); PG8_BAR;
	v_mfma_f32_16x16x32_bf16 v[124:127], v[136:139], v[156:159], v[124:127]
	s_setprio 1
	v_mfma_f32_16x16x32_bf16 v[120:123], v[144:147], v[156:159], v[120:123]
	v_mfma_f32_16x16x32_bf16 v[108:111], v[136:139], v[164:167], v[108:111]
	v_mfma_f32_16x16x32_bf16 v[104:107], v[144:147], v[164:167], v[104:107]
	v_mfma_f32_16x16x32_bf16 v[92:95], v[136:139], v[172:175], v[92:95]
	v_mfma_f32_16x16x32_bf16 v[88:91], v[144:147], v[172:175], v[88:91]
	v_mfma_f32_16x16x32_bf16 v[76:79], v[136:139], v[180:183], v[76:79]
	v_mfma_f32_16x16x32_bf16 v[72:75], v[144:147], v[180:183], v[72:75]
	v_mfma_f32_16x16x32_bf16 v[124:127], v[140:143], v[160:163], v[124:127]
	v_mfma_f32_16x16x32_bf16 v[120:123], v[148:151], v[160:163], v[120:123]
	v_mfma_f32_16x16x32_bf16 v[108:111], v[140:143], v[168:171], v[108:111]
	v_mfma_f32_16x16x32_bf16 v[104:107], v[148:151], v[168:171], v[104:107]
	v_mfma_f32_16x16x32_bf16 v[92:95], v[140:143], v[176:179], v[92:95]
	v_mfma_f32_16x16x32_bf16 v[88:91], v[148:151], v[176:179], v[88:91]
	v_mfma_f32_16x16x32_bf16 v[76:79], v[140:143], v[184:187], v[76:79]
	v_mfma_f32_16x16x32_bf16 v[72:75], v[148:151], v[184:187], v[72:75]
	v_mfma_f32_16x16x32_bf16 v[116:119], v[188:191], v[156:159], v[116:119]
	v_mfma_f32_16x16x32_bf16 v[112:115], v[196:199], v[156:159], v[112:115]
	v_mfma_f32_16x16x32_bf16 v[100:103], v[188:191], v[164:167], v[100:103]
	v_mfma_f32_16x16x32_bf16 v[96:99], v[196:199], v[164:167], v[96:99]
	v_mfma_f32_16x16x32_bf16 v[84:87], v[188:191], v[172:175], v[84:87]
	v_mfma_f32_16x16x32_bf16 v[80:83], v[196:199], v[172:175], v[80:83]
	v_mfma_f32_16x16x32_bf16 v[68:71], v[188:191], v[180:183], v[68:71]
	v_mfma_f32_16x16x32_bf16 v[64:67], v[196:199], v[180:183], v[64:67]
	v_mfma_f32_16x16x32_bf16 v[116:119], v[192:195], v[160:163], v[116:119]
	v_mfma_f32_16x16x32_bf16 v[112:115], v[200:203], v[160:163], v[112:115]
	v_mfma_f32_16x16x32_bf16 v[100:103], v[192:195], v[168:171], v[100:103]
	v_mfma_f32_16x16x32_bf16 v[96:99], v[200:203], v[168:171], v[96:99]
	v_mfma_f32_16x16x32_bf16 v[84:87], v[192:195], v[176:179], v[84:87]
	v_mfma_f32_16x16x32_bf16 v[80:83], v[200:203], v[176:179], v[80:83]
	v_mfma_f32_16x16x32_bf16 v[68:71], v[192:195], v[184:187], v[68:71]
	s_setprio 0
	v_mfma_f32_16x16x32_bf16 v[64:67], v[200:203], v[184:187], v[64:67]
	s_barrier
	ds_read_b128 v[156:159], v135 offset:16384
	ds_read_b128 v[164:167], v135 offset:18432
	ds_read_b128 v[172:175], v135 offset:20480
	ds_read_b128 v[180:183], v135 offset:22528
	ds_read_b128 v[160:163], v135 offset:17408
	ds_read_b128 v[168:171], v135 offset:19456
	ds_read_b128 v[176:179], v135 offset:21504
	ds_read_b128 v[184:187], v135 offset:23552
	s_mov_b32 m0, s55
	v_lshl_add_u64 v[204:205], s[24:25], 0, v[128:129]
	global_load_lds_dwordx4 v[204:205], off
	s_add_i32 m0, s55, 0x2000
	v_lshl_add_u64 v[204:205], s[24:25], 0, v[130:131]
	global_load_lds_dwordx4 v[204:205], off
	s_mov_b32 m0, s37
	v_lshl_add_u64 v[204:205], s[28:29], 0, v[128:129]
	global_load_lds_dwordx4 v[204:205], off
	s_mov_b32 m0, s38
	v_lshl_add_u64 v[204:205], s[28:29], 0, v[130:131]
	global_load_lds_dwordx4 v[204:205], off
	s_add_u32 s56, s24, 0x80000
	s_addc_u32 s57, s25, 0
	s_add_i32 s55, s58, s36
	s_mov_b32 m0, s55
	v_lshl_add_u64 v[204:205], s[56:57], 0, v[128:129]
	global_load_lds_dwordx4 v[204:205], off
	s_add_i32 m0, s55, 0x2000
	v_lshl_add_u64 v[204:205], s[56:57], 0, v[130:131]
	global_load_lds_dwordx4 v[204:205], off
	s_waitcnt vmcnt(6)
	s_waitcnt lgkmcnt(0)
	s_barrier
	v_mfma_f32_16x16x32_bf16 v[60:63], v[136:139], v[156:159], v[60:63]
	s_setprio 1
	v_mfma_f32_16x16x32_bf16 v[56:59], v[144:147], v[156:159], v[56:59]
	v_mfma_f32_16x16x32_bf16 v[44:47], v[136:139], v[164:167], v[44:47]
	v_mfma_f32_16x16x32_bf16 v[40:43], v[144:147], v[164:167], v[40:43]
	v_mfma_f32_16x16x32_bf16 v[28:31], v[136:139], v[172:175], v[28:31]
	v_mfma_f32_16x16x32_bf16 v[24:27], v[144:147], v[172:175], v[24:27]
	v_mfma_f32_16x16x32_bf16 v[12:15], v[136:139], v[180:183], v[12:15]
	v_mfma_f32_16x16x32_bf16 v[8:11], v[144:147], v[180:183], v[8:11]
	v_mfma_f32_16x16x32_bf16 v[60:63], v[140:143], v[160:163], v[60:63]
	v_mfma_f32_16x16x32_bf16 v[56:59], v[148:151], v[160:163], v[56:59]
	v_mfma_f32_16x16x32_bf16 v[44:47], v[140:143], v[168:171], v[44:47]
	v_mfma_f32_16x16x32_bf16 v[40:43], v[148:151], v[168:171], v[40:43]
	v_mfma_f32_16x16x32_bf16 v[28:31], v[140:143], v[176:179], v[28:31]
	v_mfma_f32_16x16x32_bf16 v[24:27], v[148:151], v[176:179], v[24:27]
	v_mfma_f32_16x16x32_bf16 v[12:15], v[140:143], v[184:187], v[12:15]
	v_mfma_f32_16x16x32_bf16 v[8:11], v[148:151], v[184:187], v[8:11]
	v_mfma_f32_16x16x32_bf16 v[52:55], v[188:191], v[156:159], v[52:55]
	v_mfma_f32_16x16x32_bf16 v[48:51], v[196:199], v[156:159], v[48:51]
	s_add_i32 s55, 0, 0x18000
	v_add_u32_e32 v148, s55, v134
	v_mfma_f32_16x16x32_bf16 v[36:39], v[188:191], v[164:167], v[36:39]
	v_mfma_f32_16x16x32_bf16 v[32:35], v[196:199], v[164:167], v[32:35]
	v_mfma_f32_16x16x32_bf16 v[20:23], v[188:191], v[172:175], v[20:23]
	v_mfma_f32_16x16x32_bf16 v[16:19], v[196:199], v[172:175], v[16:19]
	v_mfma_f32_16x16x32_bf16 v[4:7], v[188:191], v[180:183], v[4:7]
	v_mfma_f32_16x16x32_bf16 v[0:3], v[196:199], v[180:183], v[0:3]
	v_mfma_f32_16x16x32_bf16 v[52:55], v[192:195], v[160:163], v[52:55]
	v_mfma_f32_16x16x32_bf16 v[48:51], v[200:203], v[160:163], v[48:51]
	v_mfma_f32_16x16x32_bf16 v[36:39], v[192:195], v[168:171], v[36:39]
	v_mfma_f32_16x16x32_bf16 v[32:35], v[200:203], v[168:171], v[32:35]
	v_mfma_f32_16x16x32_bf16 v[20:23], v[192:195], v[176:179], v[20:23]
	v_mfma_f32_16x16x32_bf16 v[16:19], v[200:203], v[176:179], v[16:19]
	v_mfma_f32_16x16x32_bf16 v[4:7], v[192:195], v[184:187], v[4:7]
	s_setprio 0
	v_mfma_f32_16x16x32_bf16 v[0:3], v[200:203], v[184:187], v[0:3]
	s_barrier
; #define PG8_STAGE(bufoff, gbase, voff) do { _Pragma("unroll") for (int _i = 0; _i < 2; ++_i) \
;         __builtin_amdgcn_global_load_lds((const unsigned*)((const char*)(gbase) + (voff)[_i]), (LAS unsigned*)(lds + (bufoff) + ldsw + _i * 8192), 16, 0, 0); } while (0)
; #define PG8_LDA(dst, b, h) do { _Pragma("unroll") for (int m = 0; m < 4; ++m) _Pragma("unroll") for (int k = 0; k < 2; ++k) dst[m][k] = *(const LAS bf16x8*)(lds + PG8_SA(b, h) + aoff + m * 2048 + k * 1024); } while (0)
; #define PG8_LDB(dst, b, h) do { _Pragma("unroll") for (int n = 0; n < 2; ++n) _Pragma("unroll") for (int k = 0; k < 2; ++k) dst[n][k] = *(const LAS bf16x8*)(lds + PG8_SB(b, h) + boff + n * 2048 + k * 1024); } while (0)
; #define PG8_MMA(ai, bj, At, Bt) do { __builtin_amdgcn_s_setprio(1); _Pragma("unroll") for (int m = 0; m < 4; ++m) _Pragma("unroll") for (int n = 0; n < 2; ++n) _Pragma("unroll") for (int k = 0; k < 2; ++k) \
;         acc[ai][bj][m][n] = __builtin_amdgcn_mfma_f32_16x16x32_bf16(Bt[n][k], At[m][k], acc[ai][bj][m][n], 0, 0, 0); __builtin_amdgcn_s_setprio(0); } while (0)
; #define PG8_WAIT_V(n) asm volatile("s_waitcnt vmcnt(" #n ")" ::: "memory")
; #define PG8_WAIT_L(n) asm volatile("s_waitcnt lgkmcnt(" #n ")" ::: "memory")
; #define PG8_BAR __builtin_amdgcn_s_barrier()
; #define PG8_SCHED __builtin_amdgcn_sched_barrier(0)
; template <class Epi>
; __device__ __forceinline__ void gemm_phase(LAS unsigned char* lds, const Gemm g, const StaticOrder& S, const Epi& E) {
;     ...
;             PG8_LDB(B0, 1, 0); PG8_SCHED; PG8_LDA(At, 1, 0); PG8_STAGE(PG8_SA(0, 1), a2 + hstepA, voffA);
;             PG8_WAIT_L(8); PG8_BAR; PG8_WAIT_L(0); PG8_MMA(0, 0, At, B0); PG8_BAR; PG8_SCHED;
;             PG8_LDB(B1, 1, 1); PG8_STAGE(PG8_SB(1, 0), b3, voffB);
;             PG8_BAR; PG8_WAIT_L(0); PG8_MMA(0, 1, At, B1); PG8_BAR;
;             PG8_LDA(At, 1, 1); PG8_STAGE(PG8_SA(1, 0), a3, voffA);
;             PG8_BAR; PG8_WAIT_L(0); PG8_MMA(1, 0, At, B0); PG8_BAR; PG8_SCHED;
;             PG8_STAGE(PG8_SB(1, 1), b3 + hstepB, voffB);
;             PG8_WAIT_V(6); PG8_BAR; PG8_MMA(1, 1, At, B1); PG8_BAR;
	ds_read_b128 v[136:139], v148
	ds_read_b128 v[144:147], v148 offset:2048
	ds_read_b128 v[140:143], v148 offset:1024
	ds_read_b128 v[148:151], v148 offset:3072
	s_add_u32 s28, s28, 0x80000
	s_addc_u32 s29, s29, 0
	s_mov_b32 m0, s39
	v_lshl_add_u64 v[188:189], s[28:29], 0, v[128:129]
	ds_read_b128 v[156:159], v135 offset:32768
	ds_read_b128 v[164:167], v135 offset:34816
	ds_read_b128 v[172:175], v135 offset:36864
	ds_read_b128 v[180:183], v135 offset:38912
	ds_read_b128 v[160:163], v135 offset:33792
	ds_read_b128 v[168:171], v135 offset:35840
	ds_read_b128 v[176:179], v135 offset:37888
	ds_read_b128 v[184:187], v135 offset:39936
	global_load_lds_dwordx4 v[188:189], off
	s_mov_b32 m0, s40
	v_lshl_add_u64 v[188:189], s[28:29], 0, v[130:131]
	global_load_lds_dwordx4 v[188:189], off
	s_add_i32 s56, 0, 0x1c000
	s_add_u32 s28, s24, 0x4000
	s_addc_u32 s29, s25, 0
	s_add_i32 s55, s55, s36
	v_add_u32_e32 v152, s56, v134
	ds_read_b128 v[188:191], v152
	ds_read_b128 v[196:199], v152 offset:2048
	ds_read_b128 v[192:195], v152 offset:1024
	ds_read_b128 v[200:203], v152 offset:3072
	s_waitcnt lgkmcnt(0)
	s_barrier
	v_mfma_f32_16x16x32_bf16 v[124:127], v[136:139], v[156:159], v[124:127]
	s_setprio 1
	v_mfma_f32_16x16x32_bf16 v[120:123], v[144:147], v[156:159], v[120:123]
	v_mfma_f32_16x16x32_bf16 v[108:111], v[136:139], v[164:167], v[108:111]
	v_mfma_f32_16x16x32_bf16 v[104:107], v[144:147], v[164:167], v[104:107]
	v_mfma_f32_16x16x32_bf16 v[92:95], v[136:139], v[172:175], v[92:95]
	v_mfma_f32_16x16x32_bf16 v[88:91], v[144:147], v[172:175], v[88:91]
	v_mfma_f32_16x16x32_bf16 v[76:79], v[136:139], v[180:183], v[76:79]
	v_mfma_f32_16x16x32_bf16 v[72:75], v[144:147], v[180:183], v[72:75]
	v_mfma_f32_16x16x32_bf16 v[124:127], v[140:143], v[160:163], v[124:127]
	v_mfma_f32_16x16x32_bf16 v[120:123], v[148:151], v[160:163], v[120:123]
	v_mfma_f32_16x16x32_bf16 v[108:111], v[140:143], v[168:171], v[108:111]
	v_mfma_f32_16x16x32_bf16 v[104:107], v[148:151], v[168:171], v[104:107]
	v_mfma_f32_16x16x32_bf16 v[92:95], v[140:143], v[176:179], v[92:95]
	v_mfma_f32_16x16x32_bf16 v[88:91], v[148:151], v[176:179], v[88:91]
	v_mfma_f32_16x16x32_bf16 v[76:79], v[140:143], v[184:187], v[76:79]
	v_mfma_f32_16x16x32_bf16 v[72:75], v[148:151], v[184:187], v[72:75]
	v_mfma_f32_16x16x32_bf16 v[116:119], v[188:191], v[156:159], v[116:119]
	v_mfma_f32_16x16x32_bf16 v[112:115], v[196:199], v[156:159], v[112:115]
	v_mfma_f32_16x16x32_bf16 v[100:103], v[188:191], v[164:167], v[100:103]
	v_mfma_f32_16x16x32_bf16 v[96:99], v[196:199], v[164:167], v[96:99]
	v_mfma_f32_16x16x32_bf16 v[84:87], v[188:191], v[172:175], v[84:87]
	v_mfma_f32_16x16x32_bf16 v[80:83], v[196:199], v[172:175], v[80:83]
	v_mfma_f32_16x16x32_bf16 v[68:71], v[188:191], v[180:183], v[68:71]
	v_mfma_f32_16x16x32_bf16 v[64:67], v[196:199], v[180:183], v[64:67]
	v_mfma_f32_16x16x32_bf16 v[116:119], v[192:195], v[160:163], v[116:119]
	v_mfma_f32_16x16x32_bf16 v[112:115], v[200:203], v[160:163], v[112:115]
	v_mfma_f32_16x16x32_bf16 v[100:103], v[192:195], v[168:171], v[100:103]
	v_mfma_f32_16x16x32_bf16 v[96:99], v[200:203], v[168:171], v[96:99]
	v_mfma_f32_16x16x32_bf16 v[84:87], v[192:195], v[176:179], v[84:87]
	v_mfma_f32_16x16x32_bf16 v[80:83], v[200:203], v[176:179], v[80:83]
	v_mfma_f32_16x16x32_bf16 v[68:71], v[192:195], v[184:187], v[68:71]
	s_setprio 0
	v_mfma_f32_16x16x32_bf16 v[64:67], v[200:203], v[184:187], v[64:67]
	s_barrier
	ds_read_b128 v[156:159], v135 offset:49152
	ds_read_b128 v[164:167], v135 offset:51200
	ds_read_b128 v[172:175], v135 offset:53248
	ds_read_b128 v[180:183], v135 offset:55296
	ds_read_b128 v[160:163], v135 offset:50176
	ds_read_b128 v[168:171], v135 offset:52224
	ds_read_b128 v[176:179], v135 offset:54272
	ds_read_b128 v[184:187], v135 offset:56320
	s_mov_b32 m0, s55
	v_lshl_add_u64 v[204:205], s[28:29], 0, v[128:129]
	global_load_lds_dwordx4 v[204:205], off
	s_add_i32 m0, s55, 0x2000
	v_lshl_add_u64 v[204:205], s[28:29], 0, v[130:131]
	global_load_lds_dwordx4 v[204:205], off
	s_mov_b32 m0, s43
	v_lshl_add_u64 v[204:205], s[26:27], 0, v[128:129]
	global_load_lds_dwordx4 v[204:205], off
	s_mov_b32 m0, s44
	v_lshl_add_u64 v[204:205], s[26:27], 0, v[130:131]
	global_load_lds_dwordx4 v[204:205], off
	s_add_u32 s24, s24, 0x84000
	s_addc_u32 s25, s25, 0
	s_add_i32 s26, s56, s36
	s_mov_b32 m0, s26
	v_lshl_add_u64 v[204:205], s[24:25], 0, v[128:129]
	global_load_lds_dwordx4 v[204:205], off
	s_add_i32 m0, s26, 0x2000
	v_lshl_add_u64 v[204:205], s[24:25], 0, v[130:131]
	global_load_lds_dwordx4 v[204:205], off
	s_waitcnt vmcnt(6)
	s_waitcnt lgkmcnt(0)
	s_barrier
	v_mfma_f32_16x16x32_bf16 v[60:63], v[136:139], v[156:159], v[60:63]
	s_setprio 1
	v_mfma_f32_16x16x32_bf16 v[56:59], v[144:147], v[156:159], v[56:59]
	v_mfma_f32_16x16x32_bf16 v[44:47], v[136:139], v[164:167], v[44:47]
	v_mfma_f32_16x16x32_bf16 v[40:43], v[144:147], v[164:167], v[40:43]
	v_mfma_f32_16x16x32_bf16 v[28:31], v[136:139], v[172:175], v[28:31]
	v_mfma_f32_16x16x32_bf16 v[24:27], v[144:147], v[172:175], v[24:27]
	v_mfma_f32_16x16x32_bf16 v[12:15], v[136:139], v[180:183], v[12:15]
	v_mfma_f32_16x16x32_bf16 v[8:11], v[144:147], v[180:183], v[8:11]
	v_mfma_f32_16x16x32_bf16 v[60:63], v[140:143], v[160:163], v[60:63]
	v_mfma_f32_16x16x32_bf16 v[56:59], v[148:151], v[160:163], v[56:59]
	v_mfma_f32_16x16x32_bf16 v[44:47], v[140:143], v[168:171], v[44:47]
	v_mfma_f32_16x16x32_bf16 v[40:43], v[148:151], v[168:171], v[40:43]
	v_mfma_f32_16x16x32_bf16 v[28:31], v[140:143], v[176:179], v[28:31]
	v_mfma_f32_16x16x32_bf16 v[24:27], v[148:151], v[176:179], v[24:27]
	v_mfma_f32_16x16x32_bf16 v[12:15], v[140:143], v[184:187], v[12:15]
	v_mfma_f32_16x16x32_bf16 v[8:11], v[148:151], v[184:187], v[8:11]
	v_mfma_f32_16x16x32_bf16 v[52:55], v[188:191], v[156:159], v[52:55]
	v_mfma_f32_16x16x32_bf16 v[48:51], v[196:199], v[156:159], v[48:51]
	s_add_i32 s54, s54, 2
	s_add_u32 s22, s22, 0x8000
	s_addc_u32 s23, s23, 0
	s_add_u32 s51, s51, 0x8000
	s_addc_u32 s52, s52, 0
	v_mfma_f32_16x16x32_bf16 v[36:39], v[188:191], v[164:167], v[36:39]
	v_mfma_f32_16x16x32_bf16 v[32:35], v[196:199], v[164:167], v[32:35]
	v_mfma_f32_16x16x32_bf16 v[20:23], v[188:191], v[172:175], v[20:23]
	v_mfma_f32_16x16x32_bf16 v[16:19], v[196:199], v[172:175], v[16:19]
	v_mfma_f32_16x16x32_bf16 v[4:7], v[188:191], v[180:183], v[4:7]
	v_mfma_f32_16x16x32_bf16 v[0:3], v[196:199], v[180:183], v[0:3]
	v_mfma_f32_16x16x32_bf16 v[52:55], v[192:195], v[160:163], v[52:55]
	v_mfma_f32_16x16x32_bf16 v[48:51], v[200:203], v[160:163], v[48:51]
	v_mfma_f32_16x16x32_bf16 v[36:39], v[192:195], v[168:171], v[36:39]
	v_mfma_f32_16x16x32_bf16 v[32:35], v[200:203], v[168:171], v[32:35]
	v_mfma_f32_16x16x32_bf16 v[20:23], v[192:195], v[176:179], v[20:23]
	v_mfma_f32_16x16x32_bf16 v[16:19], v[200:203], v[176:179], v[16:19]
	v_mfma_f32_16x16x32_bf16 v[4:7], v[192:195], v[184:187], v[4:7]
	s_cmp_gt_u32 s54, 29
	s_setprio 0
	v_mfma_f32_16x16x32_bf16 v[0:3], v[200:203], v[184:187], v[0:3]
	s_barrier
	s_cbranch_scc0 .LBB0_141

; __device__ __forceinline__ int opaque_tid() { int t = threadIdx.x; asm volatile("" : "+v"(t)); return t; }
; #define PG8_STAGE(bufoff, gbase, voff) do { _Pragma("unroll") for (int _i = 0; _i < 2; ++_i) \
;         __builtin_amdgcn_global_load_lds((const unsigned*)((const char*)(gbase) + (voff)[_i]), (LAS unsigned*)(lds + (bufoff) + ldsw + _i * 8192), 16, 0, 0); } while (0)
; #define PG8_WAIT_V(n) asm volatile("s_waitcnt vmcnt(" #n ")" ::: "memory")
; #define PG8_BAR __builtin_amdgcn_s_barrier()
; template <class Epi>
; __device__ __forceinline__ void gemm_phase(LAS unsigned char* lds, const Gemm g, const StaticOrder& S, const Epi& E) {
;     const int tid = opaque_tid(), wid = __builtin_amdgcn_readfirstlane(tid >> 6), lane = tid & 63, wr = wid >> 2, wc = wid & 3, fr = lane & 15, fq = lane >> 4;
;     const int K = g.K, nt = K / BK;
;     unsigned voffA[2], voffB[2];
; #pragma unroll
;     for (int i = 0; i < 2; ++i) { voffA[i] = (unsigned)(tid * 16 + i * 8192); voffB[i] = voffA[i]; }
;     const size_t kstep = (size_t)HTB;
;     const size_t hstepA = (size_t)nt * HTB, hstepB = hstepA;
;     const size_t tstepA = 2 * hstepA, tstepB = tstepA;
;     const unsigned ldsw = (unsigned)wid * 1024u;
;     const int aoff = lds_byte(wr * 64 + fr, fq * 8), boff = lds_byte(wc * 32 + fr, fq * 8);
;     ...
;     const char* cA = (const char*)g.A + (size_t)cur.pm * tstepA; const char* cB = (const char*)g.Bt + (size_t)cur.pn * tstepB;
;     PG8_STAGE(PG8_SB(0, 0), cB, voffB); PG8_STAGE(PG8_SA(0, 0), cA, voffA); PG8_STAGE(PG8_SB(0, 1), cB + hstepB, voffB); PG8_STAGE(PG8_SA(0, 1), cA + hstepA, voffA);
;     if (wr == 1) PG8_BAR;
;     PG8_WAIT_V(4); PG8_BAR;
;     PG8_STAGE(PG8_SB(1, 0), cB + kstep, voffB); PG8_STAGE(PG8_SA(1, 0), cA + kstep, voffA); PG8_STAGE(PG8_SB(1, 1), cB + hstepB + kstep, voffB);
;     PG8_WAIT_V(6); PG8_BAR;
.LBB0_174:
	s_lshl_b32 s6, s6, 5
	s_and_b32 s21, s6, 0x60
	s_lshl_b32 s37, s7, 6
	s_lshl_b32 s20, s7, 13
	s_lshl_b32 s26, s21, 7
	s_add_u32 s6, s22, 0x4000
	s_addc_u32 s7, s23, 0
	s_add_i32 m0, s33, 0x18000
	v_lshl_add_u64 v[2:3], s[6:7], 0, v[152:153]
	v_mov_b32_e32 v157, v153
	s_waitcnt vmcnt(0)
	s_barrier
	global_load_lds_dwordx4 v[2:3], off
	s_add_i32 m0, s33, 0x1a000
	v_lshl_add_u64 v[2:3], s[6:7], 0, v[156:157]
	s_add_u32 s6, s24, 0x4000
	s_addc_u32 s7, s25, 0
	s_add_i32 s38, s33, 0x8000
	s_add_i32 s39, s33, 0xa000
	global_load_lds_dwordx4 v[2:3], off
	v_lshl_add_u64 v[2:3], s[6:7], 0, v[152:153]
	s_mov_b32 m0, s38
	s_add_u32 s4, s4, 0x4000
	global_load_lds_dwordx4 v[2:3], off
	v_lshl_add_u64 v[2:3], s[6:7], 0, v[156:157]
	s_mov_b32 m0, s39
	s_addc_u32 s5, s5, 0
	global_load_lds_dwordx4 v[2:3], off
	s_add_i32 m0, s33, 0x1c000
	v_lshl_add_u64 v[2:3], s[4:5], 0, v[152:153]
	global_load_lds_dwordx4 v[2:3], off
	v_lshl_add_u64 v[2:3], s[4:5], 0, v[156:157]
	s_add_i32 m0, s33, 0x1e000
	v_readlane_b32 s4, v254, 38
	global_load_lds_dwordx4 v[2:3], off
	v_lshrrev_b32_e32 v1, 1, v0
	s_ashr_i32 s41, s4, 31
	v_readlane_b32 s4, v253, 19
	v_and_b32_e32 v1, 24, v1
	s_add_i32 s40, s28, -2
	s_ashr_i32 s42, s4, 31
	v_and_b32_e32 v206, 15, v0
	v_lshlrev_b32_e32 v2, 1, v1
	v_lshlrev_b32_e32 v0, 2, v0
	s_add_u32 s43, s12, s0
	v_lshl_or_b32 v2, v206, 6, v2
	v_and_b32_e32 v0, 32, v0
	s_waitcnt vmcnt(6)
	s_addc_u32 s44, s13, s1
	v_bitop3_b32 v3, v2, s20, v0 bitop3:0xde
	s_cmp_lg_u64 s[14:15], 0
	v_bitop3_b32 v207, v2, s26, v0 bitop3:0xde
	s_cselect_b64 s[12:13], -1, 0
	v_or_b32_e32 v208, s21, v1
	v_lshl_add_u64 v[158:159], s[52:53], 0, v[152:153]
	v_lshl_add_u64 v[160:161], s[52:53], 0, v[156:157]
	s_mov_b32 s45, 0
	v_add_u32_e32 v209, 0, v3
	s_barrier
	s_branch .LBB0_176

; #define PG8_STAGE(bufoff, gbase, voff) do { _Pragma("unroll") for (int _i = 0; _i < 2; ++_i) \
;         __builtin_amdgcn_global_load_lds((const unsigned*)((const char*)(gbase) + (voff)[_i]), (LAS unsigned*)(lds + (bufoff) + ldsw + _i * 8192), 16, 0, 0); } while (0)
; #define PG8_LDA(dst, b, h) do { _Pragma("unroll") for (int m = 0; m < 4; ++m) _Pragma("unroll") for (int k = 0; k < 2; ++k) dst[m][k] = *(const LAS bf16x8*)(lds + PG8_SA(b, h) + aoff + m * 2048 + k * 1024); } while (0)
; #define PG8_LDB(dst, b, h) do { _Pragma("unroll") for (int n = 0; n < 2; ++n) _Pragma("unroll") for (int k = 0; k < 2; ++k) dst[n][k] = *(const LAS bf16x8*)(lds + PG8_SB(b, h) + boff + n * 2048 + k * 1024); } while (0)
; #define PG8_WAIT_V(n) asm volatile("s_waitcnt vmcnt(" #n ")" ::: "memory")
; #define PG8_WAIT_L(n) asm volatile("s_waitcnt lgkmcnt(" #n ")" ::: "memory")
; #define PG8_BAR __builtin_amdgcn_s_barrier()
; #define PG8_SCHED __builtin_amdgcn_sched_barrier(0)
; template <class Epi>
; __device__ __forceinline__ void gemm_phase(LAS unsigned char* lds, const Gemm g, const StaticOrder& S, const Epi& E) {
;     ...
;         const bool has_next = S.next(ui + 1, nxt);
;         const char* nA = has_next ? (const char*)g.A + (size_t)nxt.pm * tstepA : cA; const char* nB = has_next ? (const char*)g.Bt + (size_t)nxt.pn * tstepB : cB;
;         for (int t = 0; t < nt; t += 2) {
;             const bool last = (t == nt - 2);
;             const char* a1 = cA + (size_t)(t + 1) * kstep;
;             const char* a2 = last ? nA : cA + (size_t)(t + 2) * kstep; const char* b2 = last ? nB : cB + (size_t)(t + 2) * kstep;
;             const char* a3 = a2 + kstep; const char* b3 = b2 + kstep;
;             PG8_LDB(B0, 0, 0); PG8_SCHED; PG8_LDA(At, 0, 0); PG8_STAGE(PG8_SA(1, 1), a1 + hstepA, voffA);
;             PG8_WAIT_L(8); PG8_BAR; PG8_WAIT_L(0); PG8_MMA(0, 0, At, B0); PG8_BAR; PG8_SCHED;
;             PG8_LDB(B1, 0, 1); PG8_STAGE(PG8_SB(0, 0), b2, voffB);
;             PG8_BAR; PG8_WAIT_L(0); PG8_MMA(0, 1, At, B1); PG8_BAR;
;             PG8_LDA(At, 0, 1); PG8_STAGE(PG8_SA(0, 0), a2, voffA);
;             PG8_BAR; PG8_WAIT_L(0); PG8_MMA(1, 0, At, B0); PG8_BAR; PG8_SCHED;
;             PG8_STAGE(PG8_SB(0, 1), b2 + hstepB, voffB);
;             PG8_WAIT_V(6); PG8_BAR; PG8_MMA(1, 1, At, B1); PG8_BAR;
.LBB0_186:
	s_add_u32 s4, s24, 0x4000
	s_addc_u32 s5, s25, 0
	s_add_u32 s50, s22, 0x8000
	s_addc_u32 s51, s23, 0
	s_mov_b32 s22, 0
	s_add_i32 s54, s22, 2
	s_add_u32 s23, s4, 0x4000
	s_addc_u32 s24, s5, 0
	s_cmp_eq_u32 s40, s22
	s_cselect_b32 s26, s6, s23
	s_cselect_b32 s27, s7, s24
	s_cselect_b32 s24, s20, s50
	s_cselect_b32 s25, s21, s51
	s_add_u32 s22, s26, 0x4000
	s_addc_u32 s23, s27, 0
	s_add_i32 s55, 0, 0x10000
	v_add_u32_e32 v140, s55, v207
	ds_read_b128 v[128:131], v140
	ds_read_b128 v[136:139], v140 offset:2048
	ds_read_b128 v[132:135], v140 offset:1024
	ds_read_b128 v[140:143], v140 offset:3072
	v_lshl_add_u64 v[186:187], s[4:5], 0, v[158:159]
	s_add_i32 m0, s33, 0xc000
	ds_read_b128 v[144:147], v209
	ds_read_b128 v[162:165], v209 offset:2048
	ds_read_b128 v[170:173], v209 offset:4096
	ds_read_b128 v[178:181], v209 offset:6144
	ds_read_b128 v[148:151], v209 offset:1024
	ds_read_b128 v[166:169], v209 offset:3072
	ds_read_b128 v[174:177], v209 offset:5120
	ds_read_b128 v[182:185], v209 offset:7168
	global_load_lds_dwordx4 v[186:187], off
	s_add_i32 m0, s33, 0xe000
	v_lshl_add_u64 v[186:187], s[4:5], 0, v[160:161]
	global_load_lds_dwordx4 v[186:187], off
	s_add_i32 s58, 0, 0x14000
	s_add_i32 s55, s55, s31
	v_add_u32_e32 v198, s58, v207
	ds_read_b128 v[186:189], v198
	ds_read_b128 v[194:197], v198 offset:2048
	ds_read_b128 v[190:193], v198 offset:1024
	ds_read_b128 v[198:201], v198 offset:3072
	s_waitcnt lgkmcnt(0)
	s_barrier
	v_mfma_f32_16x16x32_bf16 v[124:127], v[128:131], v[144:147], 0
	s_setprio 1
	v_mfma_f32_16x16x32_bf16 v[120:123], v[136:139], v[144:147], 0
	v_mfma_f32_16x16x32_bf16 v[116:119], v[128:131], v[162:165], 0
	v_mfma_f32_16x16x32_bf16 v[112:115], v[136:139], v[162:165], 0
	v_mfma_f32_16x16x32_bf16 v[108:111], v[128:131], v[170:173], 0
	v_mfma_f32_16x16x32_bf16 v[104:107], v[136:139], v[170:173], 0
	v_mfma_f32_16x16x32_bf16 v[100:103], v[128:131], v[178:181], 0
	v_mfma_f32_16x16x32_bf16 v[96:99], v[136:139], v[178:181], 0
	v_mfma_f32_16x16x32_bf16 v[124:127], v[132:135], v[148:151], v[124:127]
	v_mfma_f32_16x16x32_bf16 v[120:123], v[140:143], v[148:151], v[120:123]
	v_mfma_f32_16x16x32_bf16 v[116:119], v[132:135], v[166:169], v[116:119]
	v_mfma_f32_16x16x32_bf16 v[112:115], v[140:143], v[166:169], v[112:115]
	v_mfma_f32_16x16x32_bf16 v[108:111], v[132:135], v[174:177], v[108:111]
	v_mfma_f32_16x16x32_bf16 v[104:107], v[140:143], v[174:177], v[104:107]
	v_mfma_f32_16x16x32_bf16 v[100:103], v[132:135], v[182:185], v[100:103]
	v_mfma_f32_16x16x32_bf16 v[96:99], v[140:143], v[182:185], v[96:99]
	v_mfma_f32_16x16x32_bf16 v[92:95], v[186:189], v[144:147], 0
	v_mfma_f32_16x16x32_bf16 v[88:91], v[194:197], v[144:147], 0
	v_mfma_f32_16x16x32_bf16 v[84:87], v[186:189], v[162:165], 0
	v_mfma_f32_16x16x32_bf16 v[80:83], v[194:197], v[162:165], 0
	v_mfma_f32_16x16x32_bf16 v[76:79], v[186:189], v[170:173], 0
	v_mfma_f32_16x16x32_bf16 v[72:75], v[194:197], v[170:173], 0
	v_mfma_f32_16x16x32_bf16 v[68:71], v[186:189], v[178:181], 0
	v_mfma_f32_16x16x32_bf16 v[64:67], v[194:197], v[178:181], 0
	v_mfma_f32_16x16x32_bf16 v[92:95], v[190:193], v[148:151], v[92:95]
	v_mfma_f32_16x16x32_bf16 v[88:91], v[198:201], v[148:151], v[88:91]
	v_mfma_f32_16x16x32_bf16 v[84:87], v[190:193], v[166:169], v[84:87]
	v_mfma_f32_16x16x32_bf16 v[80:83], v[198:201], v[166:169], v[80:83]
	v_mfma_f32_16x16x32_bf16 v[76:79], v[190:193], v[174:177], v[76:79]
	v_mfma_f32_16x16x32_bf16 v[72:75], v[198:201], v[174:177], v[72:75]
	v_mfma_f32_16x16x32_bf16 v[68:71], v[190:193], v[182:185], v[68:71]
	s_setprio 0
	v_mfma_f32_16x16x32_bf16 v[64:67], v[198:201], v[182:185], v[64:67]
	s_barrier
	ds_read_b128 v[144:147], v209 offset:16384
	ds_read_b128 v[162:165], v209 offset:18432
	ds_read_b128 v[170:173], v209 offset:20480
	ds_read_b128 v[178:181], v209 offset:22528
	ds_read_b128 v[148:151], v209 offset:17408
	ds_read_b128 v[166:169], v209 offset:19456
	ds_read_b128 v[174:177], v209 offset:21504
	ds_read_b128 v[182:185], v209 offset:23552
	s_mov_b32 m0, s55
	v_lshl_add_u64 v[202:203], s[24:25], 0, v[152:153]
	global_load_lds_dwordx4 v[202:203], off
	s_add_i32 m0, s55, 0x2000
	v_lshl_add_u64 v[202:203], s[24:25], 0, v[156:157]
	global_load_lds_dwordx4 v[202:203], off
	s_mov_b32 m0, s33
	v_lshl_add_u64 v[202:203], s[26:27], 0, v[152:153]
	global_load_lds_dwordx4 v[202:203], off
	s_mov_b32 m0, s34
	v_lshl_add_u64 v[202:203], s[26:27], 0, v[156:157]
	global_load_lds_dwordx4 v[202:203], off
	s_add_u32 s56, s24, s52
	s_addc_u32 s57, s25, 0
	s_add_i32 s55, s58, s31
	s_mov_b32 m0, s55
	v_lshl_add_u64 v[202:203], s[56:57], 0, v[152:153]
	global_load_lds_dwordx4 v[202:203], off
	s_add_i32 m0, s55, 0x2000
	v_lshl_add_u64 v[202:203], s[56:57], 0, v[156:157]
	global_load_lds_dwordx4 v[202:203], off
	s_waitcnt vmcnt(6)
	s_waitcnt lgkmcnt(0)
	s_barrier
; #define PG8_STAGE(bufoff, gbase, voff) do { _Pragma("unroll") for (int _i = 0; _i < 2; ++_i) \
;         __builtin_amdgcn_global_load_lds((const unsigned*)((const char*)(gbase) + (voff)[_i]), (LAS unsigned*)(lds + (bufoff) + ldsw + _i * 8192), 16, 0, 0); } while (0)
; #define PG8_LDA(dst, b, h) do { _Pragma("unroll") for (int m = 0; m < 4; ++m) _Pragma("unroll") for (int k = 0; k < 2; ++k) dst[m][k] = *(const LAS bf16x8*)(lds + PG8_SA(b, h) + aoff + m * 2048 + k * 1024); } while (0)
; #define PG8_LDB(dst, b, h) do { _Pragma("unroll") for (int n = 0; n < 2; ++n) _Pragma("unroll") for (int k = 0; k < 2; ++k) dst[n][k] = *(const LAS bf16x8*)(lds + PG8_SB(b, h) + boff + n * 2048 + k * 1024); } while (0)
; #define PG8_MMA(ai, bj, At, Bt) do { __builtin_amdgcn_s_setprio(1); _Pragma("unroll") for (int m = 0; m < 4; ++m) _Pragma("unroll") for (int n = 0; n < 2; ++n) _Pragma("unroll") for (int k = 0; k < 2; ++k) \
;         acc[ai][bj][m][n] = __builtin_amdgcn_mfma_f32_16x16x32_bf16(Bt[n][k], At[m][k], acc[ai][bj][m][n], 0, 0, 0); __builtin_amdgcn_s_setprio(0); } while (0)
; #define PG8_WAIT_V(n) asm volatile("s_waitcnt vmcnt(" #n ")" ::: "memory")
; #define PG8_WAIT_L(n) asm volatile("s_waitcnt lgkmcnt(" #n ")" ::: "memory")
; #define PG8_BAR __builtin_amdgcn_s_barrier()
; #define PG8_SCHED __builtin_amdgcn_sched_barrier(0)
; template <class Epi>
; __device__ __forceinline__ void gemm_phase(LAS unsigned char* lds, const Gemm g, const StaticOrder& S, const Epi& E) {
;     ...
;             PG8_WAIT_V(6); PG8_BAR; PG8_MMA(1, 1, At, B1); PG8_BAR;
;             PG8_LDB(B0, 1, 0); PG8_SCHED; PG8_LDA(At, 1, 0); PG8_STAGE(PG8_SA(0, 1), a2 + hstepA, voffA);
;             PG8_WAIT_L(8); PG8_BAR; PG8_WAIT_L(0); PG8_MMA(0, 0, At, B0); PG8_BAR; PG8_SCHED;
;             PG8_LDB(B1, 1, 1); PG8_STAGE(PG8_SB(1, 0), b3, voffB);
;             PG8_BAR; PG8_WAIT_L(0); PG8_MMA(0, 1, At, B1); PG8_BAR;
;             PG8_LDA(At, 1, 1); PG8_STAGE(PG8_SA(1, 0), a3, voffA);
;             PG8_BAR; PG8_WAIT_L(0); PG8_MMA(1, 0, At, B0); PG8_BAR; PG8_SCHED;
;             PG8_STAGE(PG8_SB(1, 1), b3 + hstepB, voffB);
;             PG8_WAIT_V(6); PG8_BAR; PG8_MMA(1, 1, At, B1); PG8_BAR;
	v_mfma_f32_16x16x32_bf16 v[60:63], v[128:131], v[144:147], 0
	s_setprio 1
	v_mfma_f32_16x16x32_bf16 v[56:59], v[136:139], v[144:147], 0
	v_mfma_f32_16x16x32_bf16 v[52:55], v[128:131], v[162:165], 0
	v_mfma_f32_16x16x32_bf16 v[48:51], v[136:139], v[162:165], 0
	v_mfma_f32_16x16x32_bf16 v[44:47], v[128:131], v[170:173], 0
	v_mfma_f32_16x16x32_bf16 v[40:43], v[136:139], v[170:173], 0
	v_mfma_f32_16x16x32_bf16 v[36:39], v[128:131], v[178:181], 0
	v_mfma_f32_16x16x32_bf16 v[32:35], v[136:139], v[178:181], 0
	v_mfma_f32_16x16x32_bf16 v[60:63], v[132:135], v[148:151], v[60:63]
	v_mfma_f32_16x16x32_bf16 v[56:59], v[140:143], v[148:151], v[56:59]
	v_mfma_f32_16x16x32_bf16 v[52:55], v[132:135], v[166:169], v[52:55]
	v_mfma_f32_16x16x32_bf16 v[48:51], v[140:143], v[166:169], v[48:51]
	v_mfma_f32_16x16x32_bf16 v[44:47], v[132:135], v[174:177], v[44:47]
	v_mfma_f32_16x16x32_bf16 v[40:43], v[140:143], v[174:177], v[40:43]
	v_mfma_f32_16x16x32_bf16 v[36:39], v[132:135], v[182:185], v[36:39]
	v_mfma_f32_16x16x32_bf16 v[32:35], v[140:143], v[182:185], v[32:35]
	v_mfma_f32_16x16x32_bf16 v[28:31], v[186:189], v[144:147], 0
	v_mfma_f32_16x16x32_bf16 v[24:27], v[194:197], v[144:147], 0
	s_add_i32 s55, 0, 0x18000
	v_add_u32_e32 v140, s55, v207
	v_mfma_f32_16x16x32_bf16 v[20:23], v[186:189], v[162:165], 0
	v_mfma_f32_16x16x32_bf16 v[16:19], v[194:197], v[162:165], 0
	v_mfma_f32_16x16x32_bf16 v[12:15], v[186:189], v[170:173], 0
	v_mfma_f32_16x16x32_bf16 v[8:11], v[194:197], v[170:173], 0
	v_mfma_f32_16x16x32_bf16 v[4:7], v[186:189], v[178:181], 0
	v_mfma_f32_16x16x32_bf16 v[0:3], v[194:197], v[178:181], 0
	v_mfma_f32_16x16x32_bf16 v[28:31], v[190:193], v[148:151], v[28:31]
	v_mfma_f32_16x16x32_bf16 v[24:27], v[198:201], v[148:151], v[24:27]
	v_mfma_f32_16x16x32_bf16 v[20:23], v[190:193], v[166:169], v[20:23]
	v_mfma_f32_16x16x32_bf16 v[16:19], v[198:201], v[166:169], v[16:19]
	v_mfma_f32_16x16x32_bf16 v[12:15], v[190:193], v[174:177], v[12:15]
	v_mfma_f32_16x16x32_bf16 v[8:11], v[198:201], v[174:177], v[8:11]
	v_mfma_f32_16x16x32_bf16 v[4:7], v[190:193], v[182:185], v[4:7]
	s_setprio 0
	v_mfma_f32_16x16x32_bf16 v[0:3], v[198:201], v[182:185], v[0:3]
	s_barrier
	ds_read_b128 v[128:131], v140
	ds_read_b128 v[136:139], v140 offset:2048
	ds_read_b128 v[132:135], v140 offset:1024
	ds_read_b128 v[140:143], v140 offset:3072
	s_add_u32 s26, s26, s52
	s_addc_u32 s27, s27, 0
	s_mov_b32 m0, s35
	v_lshl_add_u64 v[186:187], s[26:27], 0, v[152:153]
	ds_read_b128 v[144:147], v209 offset:32768
	ds_read_b128 v[162:165], v209 offset:34816
	ds_read_b128 v[170:173], v209 offset:36864
	ds_read_b128 v[178:181], v209 offset:38912
	ds_read_b128 v[148:151], v209 offset:33792
	ds_read_b128 v[166:169], v209 offset:35840
	ds_read_b128 v[174:177], v209 offset:37888
	ds_read_b128 v[182:185], v209 offset:39936
	global_load_lds_dwordx4 v[186:187], off
	s_mov_b32 m0, s36
	v_lshl_add_u64 v[186:187], s[26:27], 0, v[156:157]
	global_load_lds_dwordx4 v[186:187], off
	s_add_i32 s26, 0, 0x1c000
	s_add_u32 s24, s24, 0x4000
	s_addc_u32 s25, s25, 0
	s_add_i32 s27, s55, s31
	v_add_u32_e32 v198, s26, v207
	ds_read_b128 v[186:189], v198
	ds_read_b128 v[194:197], v198 offset:2048
	ds_read_b128 v[190:193], v198 offset:1024
	ds_read_b128 v[198:201], v198 offset:3072
	s_waitcnt lgkmcnt(0)
	s_barrier
	v_mfma_f32_16x16x32_bf16 v[124:127], v[128:131], v[144:147], v[124:127]
	s_setprio 1
	v_mfma_f32_16x16x32_bf16 v[120:123], v[136:139], v[144:147], v[120:123]
	v_mfma_f32_16x16x32_bf16 v[116:119], v[128:131], v[162:165], v[116:119]
	v_mfma_f32_16x16x32_bf16 v[112:115], v[136:139], v[162:165], v[112:115]
	v_mfma_f32_16x16x32_bf16 v[108:111], v[128:131], v[170:173], v[108:111]
	v_mfma_f32_16x16x32_bf16 v[104:107], v[136:139], v[170:173], v[104:107]
	v_mfma_f32_16x16x32_bf16 v[100:103], v[128:131], v[178:181], v[100:103]
	v_mfma_f32_16x16x32_bf16 v[96:99], v[136:139], v[178:181], v[96:99]
	v_mfma_f32_16x16x32_bf16 v[124:127], v[132:135], v[148:151], v[124:127]
	v_mfma_f32_16x16x32_bf16 v[120:123], v[140:143], v[148:151], v[120:123]
	v_mfma_f32_16x16x32_bf16 v[116:119], v[132:135], v[166:169], v[116:119]
	v_mfma_f32_16x16x32_bf16 v[112:115], v[140:143], v[166:169], v[112:115]
	v_mfma_f32_16x16x32_bf16 v[108:111], v[132:135], v[174:177], v[108:111]
	v_mfma_f32_16x16x32_bf16 v[104:107], v[140:143], v[174:177], v[104:107]
	v_mfma_f32_16x16x32_bf16 v[100:103], v[132:135], v[182:185], v[100:103]
	v_mfma_f32_16x16x32_bf16 v[96:99], v[140:143], v[182:185], v[96:99]
	v_mfma_f32_16x16x32_bf16 v[92:95], v[186:189], v[144:147], v[92:95]
	v_mfma_f32_16x16x32_bf16 v[88:91], v[194:197], v[144:147], v[88:91]
	v_mfma_f32_16x16x32_bf16 v[84:87], v[186:189], v[162:165], v[84:87]
	v_mfma_f32_16x16x32_bf16 v[80:83], v[194:197], v[162:165], v[80:83]
	v_mfma_f32_16x16x32_bf16 v[76:79], v[186:189], v[170:173], v[76:79]
	v_mfma_f32_16x16x32_bf16 v[72:75], v[194:197], v[170:173], v[72:75]
	v_mfma_f32_16x16x32_bf16 v[68:71], v[186:189], v[178:181], v[68:71]
	v_mfma_f32_16x16x32_bf16 v[64:67], v[194:197], v[178:181], v[64:67]
	v_mfma_f32_16x16x32_bf16 v[92:95], v[190:193], v[148:151], v[92:95]
	v_mfma_f32_16x16x32_bf16 v[88:91], v[198:201], v[148:151], v[88:91]
	v_mfma_f32_16x16x32_bf16 v[84:87], v[190:193], v[166:169], v[84:87]
	v_mfma_f32_16x16x32_bf16 v[80:83], v[198:201], v[166:169], v[80:83]
	v_mfma_f32_16x16x32_bf16 v[76:79], v[190:193], v[174:177], v[76:79]
	v_mfma_f32_16x16x32_bf16 v[72:75], v[198:201], v[174:177], v[72:75]
	v_mfma_f32_16x16x32_bf16 v[68:71], v[190:193], v[182:185], v[68:71]
	s_setprio 0
	v_mfma_f32_16x16x32_bf16 v[64:67], v[198:201], v[182:185], v[64:67]
	s_barrier
; #define PG8_STAGE(bufoff, gbase, voff) do { _Pragma("unroll") for (int _i = 0; _i < 2; ++_i) \
;         __builtin_amdgcn_global_load_lds((const unsigned*)((const char*)(gbase) + (voff)[_i]), (LAS unsigned*)(lds + (bufoff) + ldsw + _i * 8192), 16, 0, 0); } while (0)
; #define PG8_LDA(dst, b, h) do { _Pragma("unroll") for (int m = 0; m < 4; ++m) _Pragma("unroll") for (int k = 0; k < 2; ++k) dst[m][k] = *(const LAS bf16x8*)(lds + PG8_SA(b, h) + aoff + m * 2048 + k * 1024); } while (0)
; #define PG8_WAIT_V(n) asm volatile("s_waitcnt vmcnt(" #n ")" ::: "memory")
; #define PG8_WAIT_L(n) asm volatile("s_waitcnt lgkmcnt(" #n ")" ::: "memory")
; template <class Epi>
; __device__ __forceinline__ void gemm_phase(LAS unsigned char* lds, const Gemm g, const StaticOrder& S, const Epi& E) {
;     ...
;         for (int t = 0; t < nt; t += 2) {
;             const bool last = (t == nt - 2);
;             const char* a1 = cA + (size_t)(t + 1) * kstep;
;             const char* a2 = last ? nA : cA + (size_t)(t + 2) * kstep; const char* b2 = last ? nB : cB + (size_t)(t + 2) * kstep;
;             const char* a3 = a2 + kstep; const char* b3 = b2 + kstep;
;             PG8_LDB(B0, 0, 0); PG8_SCHED; PG8_LDA(At, 0, 0); PG8_STAGE(PG8_SA(1, 1), a1 + hstepA, voffA);
;             PG8_WAIT_L(8); PG8_BAR; PG8_WAIT_L(0); PG8_MMA(0, 0, At, B0); PG8_BAR; PG8_SCHED;
;             PG8_LDB(B1, 0, 1); PG8_STAGE(PG8_SB(0, 0), b2, voffB);
;             PG8_BAR; PG8_WAIT_L(0); PG8_MMA(0, 1, At, B1); PG8_BAR;
;             PG8_LDA(At, 0, 1); PG8_STAGE(PG8_SA(0, 0), a2, voffA);
;             PG8_BAR; PG8_WAIT_L(0); PG8_MMA(1, 0, At, B0); PG8_BAR; PG8_SCHED;
;             PG8_STAGE(PG8_SB(0, 1), b2 + hstepB, voffB);
;             PG8_WAIT_V(6); PG8_BAR; PG8_MMA(1, 1, At, B1); PG8_BAR;
;             PG8_LDB(B0, 1, 0); PG8_SCHED; PG8_LDA(At, 1, 0); PG8_STAGE(PG8_SA(0, 1), a2 + hstepA, voffA);
;             PG8_WAIT_L(8); PG8_BAR; PG8_WAIT_L(0); PG8_MMA(0, 0, At, B0); PG8_BAR; PG8_SCHED;
;             PG8_LDB(B1, 1, 1); PG8_STAGE(PG8_SB(1, 0), b3, voffB);
;             PG8_BAR; PG8_WAIT_L(0); PG8_MMA(0, 1, At, B1); PG8_BAR;
;             PG8_LDA(At, 1, 1); PG8_STAGE(PG8_SA(1, 0), a3, voffA);
;             PG8_BAR; PG8_WAIT_L(0); PG8_MMA(1, 0, At, B0); PG8_BAR; PG8_SCHED;
;             PG8_STAGE(PG8_SB(1, 1), b3 + hstepB, voffB);
;             PG8_WAIT_V(6); PG8_BAR; PG8_MMA(1, 1, At, B1); PG8_BAR;
	ds_read_b128 v[144:147], v209 offset:49152
	ds_read_b128 v[162:165], v209 offset:51200
	ds_read_b128 v[170:173], v209 offset:53248
	ds_read_b128 v[178:181], v209 offset:55296
	ds_read_b128 v[148:151], v209 offset:50176
	ds_read_b128 v[166:169], v209 offset:52224
	ds_read_b128 v[174:177], v209 offset:54272
	ds_read_b128 v[182:185], v209 offset:56320
	s_mov_b32 m0, s27
	v_lshl_add_u64 v[202:203], s[24:25], 0, v[152:153]
	global_load_lds_dwordx4 v[202:203], off
	s_add_i32 m0, s27, 0x2000
	v_lshl_add_u64 v[202:203], s[24:25], 0, v[156:157]
	global_load_lds_dwordx4 v[202:203], off
	s_mov_b32 m0, s38
	v_lshl_add_u64 v[202:203], s[22:23], 0, v[152:153]
	global_load_lds_dwordx4 v[202:203], off
	s_mov_b32 m0, s39
	v_lshl_add_u64 v[202:203], s[22:23], 0, v[156:157]
	global_load_lds_dwordx4 v[202:203], off
	s_add_u32 s22, s24, s52
	s_addc_u32 s23, s25, 0
	s_add_i32 s24, s26, s31
	s_mov_b32 m0, s24
	v_lshl_add_u64 v[202:203], s[22:23], 0, v[152:153]
	global_load_lds_dwordx4 v[202:203], off
	s_add_i32 m0, s24, 0x2000
	v_lshl_add_u64 v[202:203], s[22:23], 0, v[156:157]
	global_load_lds_dwordx4 v[202:203], off
	s_waitcnt vmcnt(6)
	s_waitcnt lgkmcnt(0)
	s_barrier
	v_mfma_f32_16x16x32_bf16 v[60:63], v[128:131], v[144:147], v[60:63]
	s_setprio 1
	v_mfma_f32_16x16x32_bf16 v[56:59], v[136:139], v[144:147], v[56:59]
	v_mfma_f32_16x16x32_bf16 v[52:55], v[128:131], v[162:165], v[52:55]
	v_mfma_f32_16x16x32_bf16 v[48:51], v[136:139], v[162:165], v[48:51]
	v_mfma_f32_16x16x32_bf16 v[44:47], v[128:131], v[170:173], v[44:47]
	v_mfma_f32_16x16x32_bf16 v[40:43], v[136:139], v[170:173], v[40:43]
	v_mfma_f32_16x16x32_bf16 v[36:39], v[128:131], v[178:181], v[36:39]
	v_mfma_f32_16x16x32_bf16 v[32:35], v[136:139], v[178:181], v[32:35]
	v_mfma_f32_16x16x32_bf16 v[60:63], v[132:135], v[148:151], v[60:63]
	v_mfma_f32_16x16x32_bf16 v[56:59], v[140:143], v[148:151], v[56:59]
	v_mfma_f32_16x16x32_bf16 v[52:55], v[132:135], v[166:169], v[52:55]
	v_mfma_f32_16x16x32_bf16 v[48:51], v[140:143], v[166:169], v[48:51]
	v_mfma_f32_16x16x32_bf16 v[44:47], v[132:135], v[174:177], v[44:47]
	v_mfma_f32_16x16x32_bf16 v[40:43], v[140:143], v[174:177], v[40:43]
	v_mfma_f32_16x16x32_bf16 v[36:39], v[132:135], v[182:185], v[36:39]
	v_mfma_f32_16x16x32_bf16 v[32:35], v[140:143], v[182:185], v[32:35]
	v_mfma_f32_16x16x32_bf16 v[28:31], v[186:189], v[144:147], v[28:31]
	v_mfma_f32_16x16x32_bf16 v[24:27], v[194:197], v[144:147], v[24:27]
	s_add_u32 s4, s4, 0x8000
	s_addc_u32 s5, s5, 0
	s_add_u32 s50, s50, 0x8000
	s_addc_u32 s51, s51, 0
	v_mfma_f32_16x16x32_bf16 v[20:23], v[186:189], v[162:165], v[20:23]
	v_mfma_f32_16x16x32_bf16 v[16:19], v[194:197], v[162:165], v[16:19]
	v_mfma_f32_16x16x32_bf16 v[12:15], v[186:189], v[170:173], v[12:15]
	v_mfma_f32_16x16x32_bf16 v[8:11], v[194:197], v[170:173], v[8:11]
	v_mfma_f32_16x16x32_bf16 v[4:7], v[186:189], v[178:181], v[4:7]
	v_mfma_f32_16x16x32_bf16 v[0:3], v[194:197], v[178:181], v[0:3]
	v_mfma_f32_16x16x32_bf16 v[28:31], v[190:193], v[148:151], v[28:31]
	v_mfma_f32_16x16x32_bf16 v[24:27], v[198:201], v[148:151], v[24:27]
	v_mfma_f32_16x16x32_bf16 v[20:23], v[190:193], v[166:169], v[20:23]
	v_mfma_f32_16x16x32_bf16 v[16:19], v[198:201], v[166:169], v[16:19]
	v_mfma_f32_16x16x32_bf16 v[12:15], v[190:193], v[174:177], v[12:15]
	v_mfma_f32_16x16x32_bf16 v[8:11], v[198:201], v[174:177], v[8:11]
	v_mfma_f32_16x16x32_bf16 v[4:7], v[190:193], v[182:185], v[4:7]
	s_cmp_ge_u32 s54, s28
	s_mov_b32 s22, s54
	s_setprio 0
	v_mfma_f32_16x16x32_bf16 v[0:3], v[198:201], v[182:185], v[0:3]
	s_barrier
	s_cbranch_scc0 .LBB0_187
	s_branch .Lpeel_done_187
.LBB0_187:
	s_add_i32 s54, s22, 2
	s_add_u32 s23, s4, 0x4000
	s_addc_u32 s24, s5, 0
	s_cmp_eq_u32 s40, s22
	s_cselect_b32 s26, s6, s23
	s_cselect_b32 s27, s7, s24
	s_cselect_b32 s24, s20, s50
	s_cselect_b32 s25, s21, s51
	s_add_u32 s22, s26, 0x4000
	s_addc_u32 s23, s27, 0
	s_add_i32 s55, 0, 0x10000
	v_add_u32_e32 v140, s55, v207
	ds_read_b128 v[128:131], v140
	ds_read_b128 v[136:139], v140 offset:2048
	ds_read_b128 v[132:135], v140 offset:1024
	ds_read_b128 v[140:143], v140 offset:3072
	v_lshl_add_u64 v[186:187], s[4:5], 0, v[158:159]
	s_add_i32 m0, s33, 0xc000
	ds_read_b128 v[144:147], v209
	ds_read_b128 v[162:165], v209 offset:2048
	ds_read_b128 v[170:173], v209 offset:4096
	ds_read_b128 v[178:181], v209 offset:6144
	ds_read_b128 v[148:151], v209 offset:1024
	ds_read_b128 v[166:169], v209 offset:3072
	ds_read_b128 v[174:177], v209 offset:5120
	ds_read_b128 v[182:185], v209 offset:7168
	global_load_lds_dwordx4 v[186:187], off
	s_add_i32 m0, s33, 0xe000
	v_lshl_add_u64 v[186:187], s[4:5], 0, v[160:161]
	global_load_lds_dwordx4 v[186:187], off
	s_add_i32 s58, 0, 0x14000
	s_add_i32 s55, s55, s31
	v_add_u32_e32 v198, s58, v207
	ds_read_b128 v[186:189], v198
	ds_read_b128 v[194:197], v198 offset:2048
	ds_read_b128 v[190:193], v198 offset:1024
	ds_read_b128 v[198:201], v198 offset:3072
	s_waitcnt lgkmcnt(0)
	s_barrier
; #define PG8_STAGE(bufoff, gbase, voff) do { _Pragma("unroll") for (int _i = 0; _i < 2; ++_i) \
;         __builtin_amdgcn_global_load_lds((const unsigned*)((const char*)(gbase) + (voff)[_i]), (LAS unsigned*)(lds + (bufoff) + ldsw + _i * 8192), 16, 0, 0); } while (0)
; #define PG8_LDA(dst, b, h) do { _Pragma("unroll") for (int m = 0; m < 4; ++m) _Pragma("unroll") for (int k = 0; k < 2; ++k) dst[m][k] = *(const LAS bf16x8*)(lds + PG8_SA(b, h) + aoff + m * 2048 + k * 1024); } while (0)
; #define PG8_LDB(dst, b, h) do { _Pragma("unroll") for (int n = 0; n < 2; ++n) _Pragma("unroll") for (int k = 0; k < 2; ++k) dst[n][k] = *(const LAS bf16x8*)(lds + PG8_SB(b, h) + boff + n * 2048 + k * 1024); } while (0)
; #define PG8_MMA(ai, bj, At, Bt) do { __builtin_amdgcn_s_setprio(1); _Pragma("unroll") for (int m = 0; m < 4; ++m) _Pragma("unroll") for (int n = 0; n < 2; ++n) _Pragma("unroll") for (int k = 0; k < 2; ++k) \
;         acc[ai][bj][m][n] = __builtin_amdgcn_mfma_f32_16x16x32_bf16(Bt[n][k], At[m][k], acc[ai][bj][m][n], 0, 0, 0); __builtin_amdgcn_s_setprio(0); } while (0)
; #define PG8_WAIT_V(n) asm volatile("s_waitcnt vmcnt(" #n ")" ::: "memory")
; #define PG8_WAIT_L(n) asm volatile("s_waitcnt lgkmcnt(" #n ")" ::: "memory")
; #define PG8_BAR __builtin_amdgcn_s_barrier()
; #define PG8_SCHED __builtin_amdgcn_sched_barrier(0)
; template <class Epi>
; __device__ __forceinline__ void gemm_phase(LAS unsigned char* lds, const Gemm g, const StaticOrder& S, const Epi& E) {
;     ...
;             PG8_WAIT_L(8); PG8_BAR; PG8_WAIT_L(0); PG8_MMA(0, 0, At, B0); PG8_BAR; PG8_SCHED;
;             PG8_LDB(B1, 0, 1); PG8_STAGE(PG8_SB(0, 0), b2, voffB);
;             PG8_BAR; PG8_WAIT_L(0); PG8_MMA(0, 1, At, B1); PG8_BAR;
;             PG8_LDA(At, 0, 1); PG8_STAGE(PG8_SA(0, 0), a2, voffA);
;             PG8_BAR; PG8_WAIT_L(0); PG8_MMA(1, 0, At, B0); PG8_BAR; PG8_SCHED;
;             PG8_STAGE(PG8_SB(0, 1), b2 + hstepB, voffB);
;             PG8_WAIT_V(6); PG8_BAR; PG8_MMA(1, 1, At, B1); PG8_BAR;
;             PG8_LDB(B0, 1, 0); PG8_SCHED; PG8_LDA(At, 1, 0); PG8_STAGE(PG8_SA(0, 1), a2 + hstepA, voffA);
;             PG8_WAIT_L(8); PG8_BAR; PG8_WAIT_L(0); PG8_MMA(0, 0, At, B0); PG8_BAR; PG8_SCHED;
	v_mfma_f32_16x16x32_bf16 v[124:127], v[128:131], v[144:147], v[124:127]
	s_setprio 1
	v_mfma_f32_16x16x32_bf16 v[120:123], v[136:139], v[144:147], v[120:123]
	v_mfma_f32_16x16x32_bf16 v[116:119], v[128:131], v[162:165], v[116:119]
	v_mfma_f32_16x16x32_bf16 v[112:115], v[136:139], v[162:165], v[112:115]
	v_mfma_f32_16x16x32_bf16 v[108:111], v[128:131], v[170:173], v[108:111]
	v_mfma_f32_16x16x32_bf16 v[104:107], v[136:139], v[170:173], v[104:107]
	v_mfma_f32_16x16x32_bf16 v[100:103], v[128:131], v[178:181], v[100:103]
	v_mfma_f32_16x16x32_bf16 v[96:99], v[136:139], v[178:181], v[96:99]
	v_mfma_f32_16x16x32_bf16 v[124:127], v[132:135], v[148:151], v[124:127]
	v_mfma_f32_16x16x32_bf16 v[120:123], v[140:143], v[148:151], v[120:123]
	v_mfma_f32_16x16x32_bf16 v[116:119], v[132:135], v[166:169], v[116:119]
	v_mfma_f32_16x16x32_bf16 v[112:115], v[140:143], v[166:169], v[112:115]
	v_mfma_f32_16x16x32_bf16 v[108:111], v[132:135], v[174:177], v[108:111]
	v_mfma_f32_16x16x32_bf16 v[104:107], v[140:143], v[174:177], v[104:107]
	v_mfma_f32_16x16x32_bf16 v[100:103], v[132:135], v[182:185], v[100:103]
	v_mfma_f32_16x16x32_bf16 v[96:99], v[140:143], v[182:185], v[96:99]
	v_mfma_f32_16x16x32_bf16 v[92:95], v[186:189], v[144:147], v[92:95]
	v_mfma_f32_16x16x32_bf16 v[88:91], v[194:197], v[144:147], v[88:91]
	v_mfma_f32_16x16x32_bf16 v[84:87], v[186:189], v[162:165], v[84:87]
	v_mfma_f32_16x16x32_bf16 v[80:83], v[194:197], v[162:165], v[80:83]
	v_mfma_f32_16x16x32_bf16 v[76:79], v[186:189], v[170:173], v[76:79]
	v_mfma_f32_16x16x32_bf16 v[72:75], v[194:197], v[170:173], v[72:75]
	v_mfma_f32_16x16x32_bf16 v[68:71], v[186:189], v[178:181], v[68:71]
	v_mfma_f32_16x16x32_bf16 v[64:67], v[194:197], v[178:181], v[64:67]
	v_mfma_f32_16x16x32_bf16 v[92:95], v[190:193], v[148:151], v[92:95]
	v_mfma_f32_16x16x32_bf16 v[88:91], v[198:201], v[148:151], v[88:91]
	v_mfma_f32_16x16x32_bf16 v[84:87], v[190:193], v[166:169], v[84:87]
	v_mfma_f32_16x16x32_bf16 v[80:83], v[198:201], v[166:169], v[80:83]
	v_mfma_f32_16x16x32_bf16 v[76:79], v[190:193], v[174:177], v[76:79]
	v_mfma_f32_16x16x32_bf16 v[72:75], v[198:201], v[174:177], v[72:75]
	v_mfma_f32_16x16x32_bf16 v[68:71], v[190:193], v[182:185], v[68:71]
	s_setprio 0
	v_mfma_f32_16x16x32_bf16 v[64:67], v[198:201], v[182:185], v[64:67]
	s_barrier
	ds_read_b128 v[144:147], v209 offset:16384
	ds_read_b128 v[162:165], v209 offset:18432
	ds_read_b128 v[170:173], v209 offset:20480
	ds_read_b128 v[178:181], v209 offset:22528
	ds_read_b128 v[148:151], v209 offset:17408
	ds_read_b128 v[166:169], v209 offset:19456
	ds_read_b128 v[174:177], v209 offset:21504
	ds_read_b128 v[182:185], v209 offset:23552
	s_mov_b32 m0, s55
	v_lshl_add_u64 v[202:203], s[24:25], 0, v[152:153]
	global_load_lds_dwordx4 v[202:203], off
	s_add_i32 m0, s55, 0x2000
	v_lshl_add_u64 v[202:203], s[24:25], 0, v[156:157]
	global_load_lds_dwordx4 v[202:203], off
	s_mov_b32 m0, s33
	v_lshl_add_u64 v[202:203], s[26:27], 0, v[152:153]
	global_load_lds_dwordx4 v[202:203], off
	s_mov_b32 m0, s34
	v_lshl_add_u64 v[202:203], s[26:27], 0, v[156:157]
	global_load_lds_dwordx4 v[202:203], off
	s_add_u32 s56, s24, s52
	s_addc_u32 s57, s25, 0
	s_add_i32 s55, s58, s31
	s_mov_b32 m0, s55
	v_lshl_add_u64 v[202:203], s[56:57], 0, v[152:153]
	global_load_lds_dwordx4 v[202:203], off
	s_add_i32 m0, s55, 0x2000
	v_lshl_add_u64 v[202:203], s[56:57], 0, v[156:157]
	global_load_lds_dwordx4 v[202:203], off
	s_waitcnt vmcnt(6)
	s_waitcnt lgkmcnt(0)
	s_barrier
	v_mfma_f32_16x16x32_bf16 v[60:63], v[128:131], v[144:147], v[60:63]
	s_setprio 1
	v_mfma_f32_16x16x32_bf16 v[56:59], v[136:139], v[144:147], v[56:59]
	v_mfma_f32_16x16x32_bf16 v[52:55], v[128:131], v[162:165], v[52:55]
	v_mfma_f32_16x16x32_bf16 v[48:51], v[136:139], v[162:165], v[48:51]
	v_mfma_f32_16x16x32_bf16 v[44:47], v[128:131], v[170:173], v[44:47]
	v_mfma_f32_16x16x32_bf16 v[40:43], v[136:139], v[170:173], v[40:43]
	v_mfma_f32_16x16x32_bf16 v[36:39], v[128:131], v[178:181], v[36:39]
	v_mfma_f32_16x16x32_bf16 v[32:35], v[136:139], v[178:181], v[32:35]
	v_mfma_f32_16x16x32_bf16 v[60:63], v[132:135], v[148:151], v[60:63]
	v_mfma_f32_16x16x32_bf16 v[56:59], v[140:143], v[148:151], v[56:59]
	v_mfma_f32_16x16x32_bf16 v[52:55], v[132:135], v[166:169], v[52:55]
	v_mfma_f32_16x16x32_bf16 v[48:51], v[140:143], v[166:169], v[48:51]
	v_mfma_f32_16x16x32_bf16 v[44:47], v[132:135], v[174:177], v[44:47]
	v_mfma_f32_16x16x32_bf16 v[40:43], v[140:143], v[174:177], v[40:43]
	v_mfma_f32_16x16x32_bf16 v[36:39], v[132:135], v[182:185], v[36:39]
	v_mfma_f32_16x16x32_bf16 v[32:35], v[140:143], v[182:185], v[32:35]
	v_mfma_f32_16x16x32_bf16 v[28:31], v[186:189], v[144:147], v[28:31]
	v_mfma_f32_16x16x32_bf16 v[24:27], v[194:197], v[144:147], v[24:27]
	s_add_i32 s55, 0, 0x18000
	v_add_u32_e32 v140, s55, v207
	v_mfma_f32_16x16x32_bf16 v[20:23], v[186:189], v[162:165], v[20:23]
	v_mfma_f32_16x16x32_bf16 v[16:19], v[194:197], v[162:165], v[16:19]
	v_mfma_f32_16x16x32_bf16 v[12:15], v[186:189], v[170:173], v[12:15]
	v_mfma_f32_16x16x32_bf16 v[8:11], v[194:197], v[170:173], v[8:11]
	v_mfma_f32_16x16x32_bf16 v[4:7], v[186:189], v[178:181], v[4:7]
	v_mfma_f32_16x16x32_bf16 v[0:3], v[194:197], v[178:181], v[0:3]
	v_mfma_f32_16x16x32_bf16 v[28:31], v[190:193], v[148:151], v[28:31]
	v_mfma_f32_16x16x32_bf16 v[24:27], v[198:201], v[148:151], v[24:27]
	v_mfma_f32_16x16x32_bf16 v[20:23], v[190:193], v[166:169], v[20:23]
	v_mfma_f32_16x16x32_bf16 v[16:19], v[198:201], v[166:169], v[16:19]
	v_mfma_f32_16x16x32_bf16 v[12:15], v[190:193], v[174:177], v[12:15]
	v_mfma_f32_16x16x32_bf16 v[8:11], v[198:201], v[174:177], v[8:11]
	v_mfma_f32_16x16x32_bf16 v[4:7], v[190:193], v[182:185], v[4:7]
	s_setprio 0
	v_mfma_f32_16x16x32_bf16 v[0:3], v[198:201], v[182:185], v[0:3]
	s_barrier
; #define PG8_STAGE(bufoff, gbase, voff) do { _Pragma("unroll") for (int _i = 0; _i < 2; ++_i) \
;         __builtin_amdgcn_global_load_lds((const unsigned*)((const char*)(gbase) + (voff)[_i]), (LAS unsigned*)(lds + (bufoff) + ldsw + _i * 8192), 16, 0, 0); } while (0)
; #define PG8_LDA(dst, b, h) do { _Pragma("unroll") for (int m = 0; m < 4; ++m) _Pragma("unroll") for (int k = 0; k < 2; ++k) dst[m][k] = *(const LAS bf16x8*)(lds + PG8_SA(b, h) + aoff + m * 2048 + k * 1024); } while (0)
; #define PG8_LDB(dst, b, h) do { _Pragma("unroll") for (int n = 0; n < 2; ++n) _Pragma("unroll") for (int k = 0; k < 2; ++k) dst[n][k] = *(const LAS bf16x8*)(lds + PG8_SB(b, h) + boff + n * 2048 + k * 1024); } while (0)
; #define PG8_MMA(ai, bj, At, Bt) do { __builtin_amdgcn_s_setprio(1); _Pragma("unroll") for (int m = 0; m < 4; ++m) _Pragma("unroll") for (int n = 0; n < 2; ++n) _Pragma("unroll") for (int k = 0; k < 2; ++k) \
;         acc[ai][bj][m][n] = __builtin_amdgcn_mfma_f32_16x16x32_bf16(Bt[n][k], At[m][k], acc[ai][bj][m][n], 0, 0, 0); __builtin_amdgcn_s_setprio(0); } while (0)
; #define PG8_WAIT_V(n) asm volatile("s_waitcnt vmcnt(" #n ")" ::: "memory")
; #define PG8_WAIT_L(n) asm volatile("s_waitcnt lgkmcnt(" #n ")" ::: "memory")
; #define PG8_BAR __builtin_amdgcn_s_barrier()
; #define PG8_SCHED __builtin_amdgcn_sched_barrier(0)
; template <class Epi>
; __device__ __forceinline__ void gemm_phase(LAS unsigned char* lds, const Gemm g, const StaticOrder& S, const Epi& E) {
;     ...
;             PG8_LDB(B0, 1, 0); PG8_SCHED; PG8_LDA(At, 1, 0); PG8_STAGE(PG8_SA(0, 1), a2 + hstepA, voffA);
;             PG8_WAIT_L(8); PG8_BAR; PG8_WAIT_L(0); PG8_MMA(0, 0, At, B0); PG8_BAR; PG8_SCHED;
;             PG8_LDB(B1, 1, 1); PG8_STAGE(PG8_SB(1, 0), b3, voffB);
;             PG8_BAR; PG8_WAIT_L(0); PG8_MMA(0, 1, At, B1); PG8_BAR;
;             PG8_LDA(At, 1, 1); PG8_STAGE(PG8_SA(1, 0), a3, voffA);
;             PG8_BAR; PG8_WAIT_L(0); PG8_MMA(1, 0, At, B0); PG8_BAR; PG8_SCHED;
;             PG8_STAGE(PG8_SB(1, 1), b3 + hstepB, voffB);
;             PG8_WAIT_V(6); PG8_BAR; PG8_MMA(1, 1, At, B1); PG8_BAR;
	ds_read_b128 v[128:131], v140
	ds_read_b128 v[136:139], v140 offset:2048
	ds_read_b128 v[132:135], v140 offset:1024
	ds_read_b128 v[140:143], v140 offset:3072
	s_add_u32 s26, s26, s52
	s_addc_u32 s27, s27, 0
	s_mov_b32 m0, s35
	v_lshl_add_u64 v[186:187], s[26:27], 0, v[152:153]
	ds_read_b128 v[144:147], v209 offset:32768
	ds_read_b128 v[162:165], v209 offset:34816
	ds_read_b128 v[170:173], v209 offset:36864
	ds_read_b128 v[178:181], v209 offset:38912
	ds_read_b128 v[148:151], v209 offset:33792
	ds_read_b128 v[166:169], v209 offset:35840
	ds_read_b128 v[174:177], v209 offset:37888
	ds_read_b128 v[182:185], v209 offset:39936
	global_load_lds_dwordx4 v[186:187], off
	s_mov_b32 m0, s36
	v_lshl_add_u64 v[186:187], s[26:27], 0, v[156:157]
	global_load_lds_dwordx4 v[186:187], off
	s_add_i32 s26, 0, 0x1c000
	s_add_u32 s24, s24, 0x4000
	s_addc_u32 s25, s25, 0
	s_add_i32 s27, s55, s31
	v_add_u32_e32 v198, s26, v207
	ds_read_b128 v[186:189], v198
	ds_read_b128 v[194:197], v198 offset:2048
	ds_read_b128 v[190:193], v198 offset:1024
	ds_read_b128 v[198:201], v198 offset:3072
	s_waitcnt lgkmcnt(0)
	s_barrier
	v_mfma_f32_16x16x32_bf16 v[124:127], v[128:131], v[144:147], v[124:127]
	s_setprio 1
	v_mfma_f32_16x16x32_bf16 v[120:123], v[136:139], v[144:147], v[120:123]
	v_mfma_f32_16x16x32_bf16 v[116:119], v[128:131], v[162:165], v[116:119]
	v_mfma_f32_16x16x32_bf16 v[112:115], v[136:139], v[162:165], v[112:115]
	v_mfma_f32_16x16x32_bf16 v[108:111], v[128:131], v[170:173], v[108:111]
	v_mfma_f32_16x16x32_bf16 v[104:107], v[136:139], v[170:173], v[104:107]
	v_mfma_f32_16x16x32_bf16 v[100:103], v[128:131], v[178:181], v[100:103]
	v_mfma_f32_16x16x32_bf16 v[96:99], v[136:139], v[178:181], v[96:99]
	v_mfma_f32_16x16x32_bf16 v[124:127], v[132:135], v[148:151], v[124:127]
	v_mfma_f32_16x16x32_bf16 v[120:123], v[140:143], v[148:151], v[120:123]
	v_mfma_f32_16x16x32_bf16 v[116:119], v[132:135], v[166:169], v[116:119]
	v_mfma_f32_16x16x32_bf16 v[112:115], v[140:143], v[166:169], v[112:115]
	v_mfma_f32_16x16x32_bf16 v[108:111], v[132:135], v[174:177], v[108:111]
	v_mfma_f32_16x16x32_bf16 v[104:107], v[140:143], v[174:177], v[104:107]
	v_mfma_f32_16x16x32_bf16 v[100:103], v[132:135], v[182:185], v[100:103]
	v_mfma_f32_16x16x32_bf16 v[96:99], v[140:143], v[182:185], v[96:99]
	v_mfma_f32_16x16x32_bf16 v[92:95], v[186:189], v[144:147], v[92:95]
	v_mfma_f32_16x16x32_bf16 v[88:91], v[194:197], v[144:147], v[88:91]
	v_mfma_f32_16x16x32_bf16 v[84:87], v[186:189], v[162:165], v[84:87]
	v_mfma_f32_16x16x32_bf16 v[80:83], v[194:197], v[162:165], v[80:83]
	v_mfma_f32_16x16x32_bf16 v[76:79], v[186:189], v[170:173], v[76:79]
	v_mfma_f32_16x16x32_bf16 v[72:75], v[194:197], v[170:173], v[72:75]
	v_mfma_f32_16x16x32_bf16 v[68:71], v[186:189], v[178:181], v[68:71]
	v_mfma_f32_16x16x32_bf16 v[64:67], v[194:197], v[178:181], v[64:67]
	v_mfma_f32_16x16x32_bf16 v[92:95], v[190:193], v[148:151], v[92:95]
	v_mfma_f32_16x16x32_bf16 v[88:91], v[198:201], v[148:151], v[88:91]
	v_mfma_f32_16x16x32_bf16 v[84:87], v[190:193], v[166:169], v[84:87]
	v_mfma_f32_16x16x32_bf16 v[80:83], v[198:201], v[166:169], v[80:83]
	v_mfma_f32_16x16x32_bf16 v[76:79], v[190:193], v[174:177], v[76:79]
	v_mfma_f32_16x16x32_bf16 v[72:75], v[198:201], v[174:177], v[72:75]
	v_mfma_f32_16x16x32_bf16 v[68:71], v[190:193], v[182:185], v[68:71]
	s_setprio 0
	v_mfma_f32_16x16x32_bf16 v[64:67], v[198:201], v[182:185], v[64:67]
	s_barrier
	ds_read_b128 v[144:147], v209 offset:49152
	ds_read_b128 v[162:165], v209 offset:51200
	ds_read_b128 v[170:173], v209 offset:53248
	ds_read_b128 v[178:181], v209 offset:55296
	ds_read_b128 v[148:151], v209 offset:50176
	ds_read_b128 v[166:169], v209 offset:52224
	ds_read_b128 v[174:177], v209 offset:54272
	ds_read_b128 v[182:185], v209 offset:56320
	s_mov_b32 m0, s27
	v_lshl_add_u64 v[202:203], s[24:25], 0, v[152:153]
	global_load_lds_dwordx4 v[202:203], off
	s_add_i32 m0, s27, 0x2000
	v_lshl_add_u64 v[202:203], s[24:25], 0, v[156:157]
	global_load_lds_dwordx4 v[202:203], off
	s_mov_b32 m0, s38
	v_lshl_add_u64 v[202:203], s[22:23], 0, v[152:153]
	global_load_lds_dwordx4 v[202:203], off
	s_mov_b32 m0, s39
	v_lshl_add_u64 v[202:203], s[22:23], 0, v[156:157]
	global_load_lds_dwordx4 v[202:203], off
	s_add_u32 s22, s24, s52
	s_addc_u32 s23, s25, 0
	s_add_i32 s24, s26, s31
	s_mov_b32 m0, s24
	v_lshl_add_u64 v[202:203], s[22:23], 0, v[152:153]
	global_load_lds_dwordx4 v[202:203], off
	s_add_i32 m0, s24, 0x2000
	v_lshl_add_u64 v[202:203], s[22:23], 0, v[156:157]
	global_load_lds_dwordx4 v[202:203], off
	s_waitcnt vmcnt(6)
	s_waitcnt lgkmcnt(0)
	s_barrier
	v_mfma_f32_16x16x32_bf16 v[60:63], v[128:131], v[144:147], v[60:63]
	s_setprio 1
	v_mfma_f32_16x16x32_bf16 v[56:59], v[136:139], v[144:147], v[56:59]
	v_mfma_f32_16x16x32_bf16 v[52:55], v[128:131], v[162:165], v[52:55]
	v_mfma_f32_16x16x32_bf16 v[48:51], v[136:139], v[162:165], v[48:51]
	v_mfma_f32_16x16x32_bf16 v[44:47], v[128:131], v[170:173], v[44:47]
	v_mfma_f32_16x16x32_bf16 v[40:43], v[136:139], v[170:173], v[40:43]
	v_mfma_f32_16x16x32_bf16 v[36:39], v[128:131], v[178:181], v[36:39]
	v_mfma_f32_16x16x32_bf16 v[32:35], v[136:139], v[178:181], v[32:35]
	v_mfma_f32_16x16x32_bf16 v[60:63], v[132:135], v[148:151], v[60:63]
	v_mfma_f32_16x16x32_bf16 v[56:59], v[140:143], v[148:151], v[56:59]
	v_mfma_f32_16x16x32_bf16 v[52:55], v[132:135], v[166:169], v[52:55]
	v_mfma_f32_16x16x32_bf16 v[48:51], v[140:143], v[166:169], v[48:51]
	v_mfma_f32_16x16x32_bf16 v[44:47], v[132:135], v[174:177], v[44:47]
	v_mfma_f32_16x16x32_bf16 v[40:43], v[140:143], v[174:177], v[40:43]
	v_mfma_f32_16x16x32_bf16 v[36:39], v[132:135], v[182:185], v[36:39]
	v_mfma_f32_16x16x32_bf16 v[32:35], v[140:143], v[182:185], v[32:35]
	v_mfma_f32_16x16x32_bf16 v[28:31], v[186:189], v[144:147], v[28:31]
	v_mfma_f32_16x16x32_bf16 v[24:27], v[194:197], v[144:147], v[24:27]
	s_add_u32 s4, s4, 0x8000
	s_addc_u32 s5, s5, 0
	s_add_u32 s50, s50, 0x8000
	s_addc_u32 s51, s51, 0
	v_mfma_f32_16x16x32_bf16 v[20:23], v[186:189], v[162:165], v[20:23]
	v_mfma_f32_16x16x32_bf16 v[16:19], v[194:197], v[162:165], v[16:19]
	v_mfma_f32_16x16x32_bf16 v[12:15], v[186:189], v[170:173], v[12:15]
	v_mfma_f32_16x16x32_bf16 v[8:11], v[194:197], v[170:173], v[8:11]
	v_mfma_f32_16x16x32_bf16 v[4:7], v[186:189], v[178:181], v[4:7]
	v_mfma_f32_16x16x32_bf16 v[0:3], v[194:197], v[178:181], v[0:3]
	v_mfma_f32_16x16x32_bf16 v[28:31], v[190:193], v[148:151], v[28:31]
	v_mfma_f32_16x16x32_bf16 v[24:27], v[198:201], v[148:151], v[24:27]
	v_mfma_f32_16x16x32_bf16 v[20:23], v[190:193], v[166:169], v[20:23]
	v_mfma_f32_16x16x32_bf16 v[16:19], v[198:201], v[166:169], v[16:19]
	v_mfma_f32_16x16x32_bf16 v[12:15], v[190:193], v[174:177], v[12:15]
	v_mfma_f32_16x16x32_bf16 v[8:11], v[198:201], v[174:177], v[8:11]
	v_mfma_f32_16x16x32_bf16 v[4:7], v[190:193], v[182:185], v[4:7]
	s_cmp_ge_u32 s54, s28
	s_mov_b32 s22, s54
	s_setprio 0
	v_mfma_f32_16x16x32_bf16 v[0:3], v[198:201], v[182:185], v[0:3]
	s_barrier
	s_cbranch_scc0 .LBB0_187

; #define PG8_STAGE(bufoff, gbase, voff) do { _Pragma("unroll") for (int _i = 0; _i < 2; ++_i) \
;         __builtin_amdgcn_global_load_lds((const unsigned*)((const char*)(gbase) + (voff)[_i]), (LAS unsigned*)(lds + (bufoff) + ldsw + _i * 8192), 16, 0, 0); } while (0)
; #define PG8_WAIT_V(n) asm volatile("s_waitcnt vmcnt(" #n ")" ::: "memory")
; #define PG8_BAR __builtin_amdgcn_s_barrier()
; template <class Epi>
; __device__ __forceinline__ void gemm_phase(LAS unsigned char* lds, const Gemm g, const StaticOrder& S, const Epi& E) {
;     ...
;     const char* cA = (const char*)g.A + (size_t)cur.pm * tstepA; const char* cB = (const char*)g.Bt + (size_t)cur.pn * tstepB;
;     PG8_STAGE(PG8_SB(0, 0), cB, voffB); PG8_STAGE(PG8_SA(0, 0), cA, voffA); PG8_STAGE(PG8_SB(0, 1), cB + hstepB, voffB); PG8_STAGE(PG8_SA(0, 1), cA + hstepA, voffA);
;     if (wr == 1) PG8_BAR;
;     PG8_WAIT_V(4); PG8_BAR;
;     PG8_STAGE(PG8_SB(1, 0), cB + kstep, voffB); PG8_STAGE(PG8_SA(1, 0), cA + kstep, voffA); PG8_STAGE(PG8_SB(1, 1), cB + hstepB + kstep, voffB);
;     PG8_WAIT_V(6); PG8_BAR;
;     __device__ __forceinline__ void operator()(const f32x4 (&acc)[2][2][4][2], const Unit& u, int wr, int wc, int fr, int fq) const {
;         const int row0 = u.pm * BM + wr * 64 + fr, j0 = wc * 16 + 4 * fq, colb = u.pn * BM + j0;
;         if (u.pn < 8) {
;             const float sc = (u.pn < 4) ? QSCALE : 1.0f;
; #pragma unroll
;             for (int ai = 0; ai < 2; ++ai) {
;                 f32x4 csv[4], snv[4];
; #pragma unroll
;                 for (int m = 0; m < 4; ++m) { const int pos = (row0 + ai * HALF + m * 16) & (SEQ - 1); csv[m] = *(const f32x4*)(cosT + pos * 64 + j0); snv[m] = *(const f32x4*)(sinT + pos * 64 + j0); }
.LBB0_242:
	s_and_b32 s4, s2, 3
	s_lshl_b32 s5, s1, 13
	s_lshl_b32 s6, s4, 12
	s_add_u32 s2, s14, 0x4000
	v_mov_b32_e32 v157, v153
	s_addc_u32 s3, s15, 0
	s_add_i32 m0, s25, 0x18000
	v_lshl_add_u64 v[2:3], s[2:3], 0, v[156:157]
	v_mov_b32_e32 v159, v153
	s_waitcnt vmcnt(0)
	s_barrier
	global_load_lds_dwordx4 v[2:3], off
	s_add_i32 m0, s25, 0x1a000
	v_lshl_add_u64 v[2:3], s[2:3], 0, v[158:159]
	s_add_u32 s2, s12, 0x4000
	s_addc_u32 s3, s13, 0
	s_add_i32 s29, s25, 0x8000
	global_load_lds_dwordx4 v[2:3], off
	v_lshl_add_u64 v[2:3], s[2:3], 0, v[156:157]
	s_mov_b32 m0, s29
	s_add_i32 s30, s25, 0xa000
	global_load_lds_dwordx4 v[2:3], off
	v_lshl_add_u64 v[2:3], s[2:3], 0, v[158:159]
	s_add_u32 s2, s14, 0x84000
	s_mov_b32 m0, s30
	s_addc_u32 s3, s15, 0
	global_load_lds_dwordx4 v[2:3], off
	s_add_i32 m0, s25, 0x1c000
	v_lshl_add_u64 v[2:3], s[2:3], 0, v[156:157]
	global_load_lds_dwordx4 v[2:3], off
	v_lshl_add_u64 v[2:3], s[2:3], 0, v[158:159]
	s_add_i32 m0, s25, 0x1e000
	v_and_b32_e32 v1, 15, v0
	global_load_lds_dwordx4 v[2:3], off
	v_bfe_u32 v2, v0, 4, 2
	v_lshlrev_b32_e32 v3, 4, v2
	v_lshlrev_b32_e32 v0, 2, v0
	v_lshl_or_b32 v165, s1, 6, v1
	v_lshl_or_b32 v1, v1, 6, v3
	v_and_b32_e32 v0, 32, v0
	s_sext_i32_i8 s34, s0
	v_bitop3_b32 v3, v1, s5, v0 bitop3:0xde
	v_bitop3_b32 v170, v1, s6, v0 bitop3:0xde
	v_lshlrev_b32_e32 v0, 2, v2
	v_readlane_b32 s0, v254, 38
	v_lshl_or_b32 v171, s4, 4, v0
	s_ashr_i32 s31, s0, 31
	v_readlane_b32 s0, v253, 3
	v_lshlrev_b32_e32 v152, 2, v171
	v_readlane_b32 s1, v253, 4
	s_waitcnt vmcnt(6)
	s_mov_b32 s33, 0
	v_add_u32_e32 v172, 0, v3
	v_lshl_add_u64 v[160:161], s[0:1], 0, v[152:153]
	v_readlane_b32 s0, v253, 5
	v_readlane_b32 s1, v253, 6
	s_barrier
	s_nop 0
	v_lshl_add_u64 v[162:163], s[0:1], 0, v[152:153]
	s_branch .LBB0_244

; #define PG8_STAGE(bufoff, gbase, voff) do { _Pragma("unroll") for (int _i = 0; _i < 2; ++_i) \
;         __builtin_amdgcn_global_load_lds((const unsigned*)((const char*)(gbase) + (voff)[_i]), (LAS unsigned*)(lds + (bufoff) + ldsw + _i * 8192), 16, 0, 0); } while (0)
; #define PG8_LDA(dst, b, h) do { _Pragma("unroll") for (int m = 0; m < 4; ++m) _Pragma("unroll") for (int k = 0; k < 2; ++k) dst[m][k] = *(const LAS bf16x8*)(lds + PG8_SA(b, h) + aoff + m * 2048 + k * 1024); } while (0)
; #define PG8_LDB(dst, b, h) do { _Pragma("unroll") for (int n = 0; n < 2; ++n) _Pragma("unroll") for (int k = 0; k < 2; ++k) dst[n][k] = *(const LAS bf16x8*)(lds + PG8_SB(b, h) + boff + n * 2048 + k * 1024); } while (0)
; #define PG8_WAIT_V(n) asm volatile("s_waitcnt vmcnt(" #n ")" ::: "memory")
; #define PG8_WAIT_L(n) asm volatile("s_waitcnt lgkmcnt(" #n ")" ::: "memory")
; #define PG8_BAR __builtin_amdgcn_s_barrier()
; #define PG8_SCHED __builtin_amdgcn_sched_barrier(0)
; template <class Epi>
; __device__ __forceinline__ void gemm_phase(LAS unsigned char* lds, const Gemm g, const StaticOrder& S, const Epi& E) {
;     ...
;         const bool has_next = S.next(ui + 1, nxt);
;         const char* nA = has_next ? (const char*)g.A + (size_t)nxt.pm * tstepA : cA; const char* nB = has_next ? (const char*)g.Bt + (size_t)nxt.pn * tstepB : cB;
;         for (int t = 0; t < nt; t += 2) {
;             const bool last = (t == nt - 2);
;             const char* a1 = cA + (size_t)(t + 1) * kstep;
;             const char* a2 = last ? nA : cA + (size_t)(t + 2) * kstep; const char* b2 = last ? nB : cB + (size_t)(t + 2) * kstep;
;             const char* a3 = a2 + kstep; const char* b3 = b2 + kstep;
;             PG8_LDB(B0, 0, 0); PG8_SCHED; PG8_LDA(At, 0, 0); PG8_STAGE(PG8_SA(1, 1), a1 + hstepA, voffA);
;             PG8_WAIT_L(8); PG8_BAR; PG8_WAIT_L(0); PG8_MMA(0, 0, At, B0); PG8_BAR; PG8_SCHED;
;             PG8_LDB(B1, 0, 1); PG8_STAGE(PG8_SB(0, 0), b2, voffB);
;             PG8_BAR; PG8_WAIT_L(0); PG8_MMA(0, 1, At, B1); PG8_BAR;
;             PG8_LDA(At, 0, 1); PG8_STAGE(PG8_SA(0, 0), a2, voffA);
;             PG8_BAR; PG8_WAIT_L(0); PG8_MMA(1, 0, At, B0); PG8_BAR; PG8_SCHED;
;             PG8_STAGE(PG8_SB(0, 1), b2 + hstepB, voffB);
;             PG8_WAIT_V(6); PG8_BAR; PG8_MMA(1, 1, At, B1); PG8_BAR;
.LBB0_246:
	s_ashr_i32 s5, s4, 31
	v_cmp_lt_i64_e32 vcc, s[6:7], v[154:155]
	s_lshl_b64 s[6:7], s[4:5], 20
	v_readlane_b32 s8, v252, 53
	v_readlane_b32 s9, v252, 54
	s_add_u32 s6, s8, s6
	s_addc_u32 s7, s9, s7
	s_and_b64 s[8:9], vcc, exec
	s_cselect_b32 s5, s7, s13
	s_cselect_b32 s11, s6, s12
	s_ashr_i32 s3, s2, 31
	s_lshl_b64 s[8:9], s[2:3], 20
	s_add_u32 s8, s21, s8
	s_addc_u32 s9, s22, s9
	s_and_b64 s[16:17], vcc, exec
	s_cselect_b32 s3, s9, s15
	s_cselect_b32 s35, s8, s14
	s_add_u32 s12, s12, 0x84000
	s_addc_u32 s13, s13, 0
	s_add_u32 s36, s14, 0x8000
	s_addc_u32 s37, s15, 0
	s_mov_b32 s38, -2
	s_add_u32 s14, s12, 0xfff84000
	s_addc_u32 s15, s13, -1
	s_cmp_eq_u32 s38, 28
	s_cselect_b32 s18, s11, s14
	s_cselect_b32 s19, s5, s15
	s_cselect_b32 s14, s35, s36
	s_cselect_b32 s15, s3, s37
	s_add_u32 s16, s18, 0x4000
	s_addc_u32 s17, s19, 0
	s_add_i32 s39, 0, 0x10000
	v_add_u32_e32 v140, s39, v170
	ds_read_b128 v[128:131], v140
	ds_read_b128 v[136:139], v140 offset:2048
	ds_read_b128 v[132:135], v140 offset:1024
	ds_read_b128 v[140:143], v140 offset:3072
	v_lshl_add_u64 v[194:195], s[12:13], 0, v[156:157]
	s_add_i32 m0, s25, 0xc000
	ds_read_b128 v[144:147], v172
	ds_read_b128 v[166:169], v172 offset:2048
	ds_read_b128 v[178:181], v172 offset:4096
	ds_read_b128 v[186:189], v172 offset:6144
	ds_read_b128 v[148:151], v172 offset:1024
	ds_read_b128 v[174:177], v172 offset:3072
	ds_read_b128 v[182:185], v172 offset:5120
	ds_read_b128 v[190:193], v172 offset:7168
	global_load_lds_dwordx4 v[194:195], off
	s_add_i32 m0, s25, 0xe000
	v_lshl_add_u64 v[194:195], s[12:13], 0, v[158:159]
	global_load_lds_dwordx4 v[194:195], off
	s_add_i32 s42, 0, 0x14000
	s_add_i32 s39, s39, s23
	v_add_u32_e32 v152, s42, v170
	ds_read_b128 v[194:197], v152
	ds_read_b128 v[202:205], v152 offset:2048
	ds_read_b128 v[198:201], v152 offset:1024
	ds_read_b128 v[206:209], v152 offset:3072
	s_waitcnt lgkmcnt(0)
	s_barrier
	v_mfma_f32_16x16x32_bf16 v[124:127], v[128:131], v[144:147], 0
	s_setprio 1
	v_mfma_f32_16x16x32_bf16 v[120:123], v[136:139], v[144:147], 0
	v_mfma_f32_16x16x32_bf16 v[108:111], v[128:131], v[166:169], 0
	v_mfma_f32_16x16x32_bf16 v[104:107], v[136:139], v[166:169], 0
	v_mfma_f32_16x16x32_bf16 v[92:95], v[128:131], v[178:181], 0
	v_mfma_f32_16x16x32_bf16 v[88:91], v[136:139], v[178:181], 0
	v_mfma_f32_16x16x32_bf16 v[76:79], v[128:131], v[186:189], 0
	v_mfma_f32_16x16x32_bf16 v[72:75], v[136:139], v[186:189], 0
	v_mfma_f32_16x16x32_bf16 v[124:127], v[132:135], v[148:151], v[124:127]
	v_mfma_f32_16x16x32_bf16 v[120:123], v[140:143], v[148:151], v[120:123]
	v_mfma_f32_16x16x32_bf16 v[108:111], v[132:135], v[174:177], v[108:111]
	v_mfma_f32_16x16x32_bf16 v[104:107], v[140:143], v[174:177], v[104:107]
	v_mfma_f32_16x16x32_bf16 v[92:95], v[132:135], v[182:185], v[92:95]
	v_mfma_f32_16x16x32_bf16 v[88:91], v[140:143], v[182:185], v[88:91]
	v_mfma_f32_16x16x32_bf16 v[76:79], v[132:135], v[190:193], v[76:79]
	v_mfma_f32_16x16x32_bf16 v[72:75], v[140:143], v[190:193], v[72:75]
	v_mfma_f32_16x16x32_bf16 v[116:119], v[194:197], v[144:147], 0
	v_mfma_f32_16x16x32_bf16 v[112:115], v[202:205], v[144:147], 0
	v_mfma_f32_16x16x32_bf16 v[100:103], v[194:197], v[166:169], 0
	v_mfma_f32_16x16x32_bf16 v[96:99], v[202:205], v[166:169], 0
	v_mfma_f32_16x16x32_bf16 v[84:87], v[194:197], v[178:181], 0
	v_mfma_f32_16x16x32_bf16 v[80:83], v[202:205], v[178:181], 0
	v_mfma_f32_16x16x32_bf16 v[68:71], v[194:197], v[186:189], 0
	v_mfma_f32_16x16x32_bf16 v[64:67], v[202:205], v[186:189], 0
	v_mfma_f32_16x16x32_bf16 v[116:119], v[198:201], v[148:151], v[116:119]
	v_mfma_f32_16x16x32_bf16 v[112:115], v[206:209], v[148:151], v[112:115]
	v_mfma_f32_16x16x32_bf16 v[100:103], v[198:201], v[174:177], v[100:103]
	v_mfma_f32_16x16x32_bf16 v[96:99], v[206:209], v[174:177], v[96:99]
	v_mfma_f32_16x16x32_bf16 v[84:87], v[198:201], v[182:185], v[84:87]
	v_mfma_f32_16x16x32_bf16 v[80:83], v[206:209], v[182:185], v[80:83]
	v_mfma_f32_16x16x32_bf16 v[68:71], v[198:201], v[190:193], v[68:71]
	s_setprio 0
	v_mfma_f32_16x16x32_bf16 v[64:67], v[206:209], v[190:193], v[64:67]
	s_barrier
	ds_read_b128 v[144:147], v172 offset:16384
	ds_read_b128 v[166:169], v172 offset:18432
	ds_read_b128 v[178:181], v172 offset:20480
	ds_read_b128 v[186:189], v172 offset:22528
	ds_read_b128 v[148:151], v172 offset:17408
	ds_read_b128 v[174:177], v172 offset:19456
	ds_read_b128 v[182:185], v172 offset:21504
	ds_read_b128 v[190:193], v172 offset:23552
	s_mov_b32 m0, s39
	v_lshl_add_u64 v[210:211], s[14:15], 0, v[156:157]
	global_load_lds_dwordx4 v[210:211], off
	s_add_i32 m0, s39, 0x2000
	v_lshl_add_u64 v[210:211], s[14:15], 0, v[158:159]
	global_load_lds_dwordx4 v[210:211], off
	s_mov_b32 m0, s25
	v_lshl_add_u64 v[210:211], s[18:19], 0, v[156:157]
	global_load_lds_dwordx4 v[210:211], off
	s_mov_b32 m0, s26
	v_lshl_add_u64 v[210:211], s[18:19], 0, v[158:159]
	global_load_lds_dwordx4 v[210:211], off
	s_add_u32 s40, s14, 0x80000
	s_addc_u32 s41, s15, 0
	s_add_i32 s39, s42, s23
	s_mov_b32 m0, s39
	v_lshl_add_u64 v[210:211], s[40:41], 0, v[156:157]
	global_load_lds_dwordx4 v[210:211], off
	s_add_i32 m0, s39, 0x2000
	v_lshl_add_u64 v[210:211], s[40:41], 0, v[158:159]
	global_load_lds_dwordx4 v[210:211], off
	s_waitcnt vmcnt(6)
	s_waitcnt lgkmcnt(0)
	s_barrier
; #define PG8_STAGE(bufoff, gbase, voff) do { _Pragma("unroll") for (int _i = 0; _i < 2; ++_i) \
;         __builtin_amdgcn_global_load_lds((const unsigned*)((const char*)(gbase) + (voff)[_i]), (LAS unsigned*)(lds + (bufoff) + ldsw + _i * 8192), 16, 0, 0); } while (0)
; #define PG8_LDA(dst, b, h) do { _Pragma("unroll") for (int m = 0; m < 4; ++m) _Pragma("unroll") for (int k = 0; k < 2; ++k) dst[m][k] = *(const LAS bf16x8*)(lds + PG8_SA(b, h) + aoff + m * 2048 + k * 1024); } while (0)
; #define PG8_LDB(dst, b, h) do { _Pragma("unroll") for (int n = 0; n < 2; ++n) _Pragma("unroll") for (int k = 0; k < 2; ++k) dst[n][k] = *(const LAS bf16x8*)(lds + PG8_SB(b, h) + boff + n * 2048 + k * 1024); } while (0)
; #define PG8_MMA(ai, bj, At, Bt) do { __builtin_amdgcn_s_setprio(1); _Pragma("unroll") for (int m = 0; m < 4; ++m) _Pragma("unroll") for (int n = 0; n < 2; ++n) _Pragma("unroll") for (int k = 0; k < 2; ++k) \
;         acc[ai][bj][m][n] = __builtin_amdgcn_mfma_f32_16x16x32_bf16(Bt[n][k], At[m][k], acc[ai][bj][m][n], 0, 0, 0); __builtin_amdgcn_s_setprio(0); } while (0)
; #define PG8_WAIT_V(n) asm volatile("s_waitcnt vmcnt(" #n ")" ::: "memory")
; #define PG8_WAIT_L(n) asm volatile("s_waitcnt lgkmcnt(" #n ")" ::: "memory")
; #define PG8_BAR __builtin_amdgcn_s_barrier()
; #define PG8_SCHED __builtin_amdgcn_sched_barrier(0)
; template <class Epi>
; __device__ __forceinline__ void gemm_phase(LAS unsigned char* lds, const Gemm g, const StaticOrder& S, const Epi& E) {
;     ...
;             PG8_WAIT_V(6); PG8_BAR; PG8_MMA(1, 1, At, B1); PG8_BAR;
;             PG8_LDB(B0, 1, 0); PG8_SCHED; PG8_LDA(At, 1, 0); PG8_STAGE(PG8_SA(0, 1), a2 + hstepA, voffA);
;             PG8_WAIT_L(8); PG8_BAR; PG8_WAIT_L(0); PG8_MMA(0, 0, At, B0); PG8_BAR; PG8_SCHED;
;             PG8_LDB(B1, 1, 1); PG8_STAGE(PG8_SB(1, 0), b3, voffB);
;             PG8_BAR; PG8_WAIT_L(0); PG8_MMA(0, 1, At, B1); PG8_BAR;
;             PG8_LDA(At, 1, 1); PG8_STAGE(PG8_SA(1, 0), a3, voffA);
;             PG8_BAR; PG8_WAIT_L(0); PG8_MMA(1, 0, At, B0); PG8_BAR; PG8_SCHED;
;             PG8_STAGE(PG8_SB(1, 1), b3 + hstepB, voffB);
;             PG8_WAIT_V(6); PG8_BAR; PG8_MMA(1, 1, At, B1); PG8_BAR;
	v_mfma_f32_16x16x32_bf16 v[60:63], v[128:131], v[144:147], 0
	s_setprio 1
	v_mfma_f32_16x16x32_bf16 v[56:59], v[136:139], v[144:147], 0
	v_mfma_f32_16x16x32_bf16 v[44:47], v[128:131], v[166:169], 0
	v_mfma_f32_16x16x32_bf16 v[40:43], v[136:139], v[166:169], 0
	v_mfma_f32_16x16x32_bf16 v[28:31], v[128:131], v[178:181], 0
	v_mfma_f32_16x16x32_bf16 v[24:27], v[136:139], v[178:181], 0
	v_mfma_f32_16x16x32_bf16 v[12:15], v[128:131], v[186:189], 0
	v_mfma_f32_16x16x32_bf16 v[8:11], v[136:139], v[186:189], 0
	v_mfma_f32_16x16x32_bf16 v[60:63], v[132:135], v[148:151], v[60:63]
	v_mfma_f32_16x16x32_bf16 v[56:59], v[140:143], v[148:151], v[56:59]
	v_mfma_f32_16x16x32_bf16 v[44:47], v[132:135], v[174:177], v[44:47]
	v_mfma_f32_16x16x32_bf16 v[40:43], v[140:143], v[174:177], v[40:43]
	v_mfma_f32_16x16x32_bf16 v[28:31], v[132:135], v[182:185], v[28:31]
	v_mfma_f32_16x16x32_bf16 v[24:27], v[140:143], v[182:185], v[24:27]
	v_mfma_f32_16x16x32_bf16 v[12:15], v[132:135], v[190:193], v[12:15]
	v_mfma_f32_16x16x32_bf16 v[8:11], v[140:143], v[190:193], v[8:11]
	v_mfma_f32_16x16x32_bf16 v[52:55], v[194:197], v[144:147], 0
	v_mfma_f32_16x16x32_bf16 v[48:51], v[202:205], v[144:147], 0
	s_add_i32 s39, 0, 0x18000
	v_add_u32_e32 v140, s39, v170
	v_mfma_f32_16x16x32_bf16 v[36:39], v[194:197], v[166:169], 0
	v_mfma_f32_16x16x32_bf16 v[32:35], v[202:205], v[166:169], 0
	v_mfma_f32_16x16x32_bf16 v[20:23], v[194:197], v[178:181], 0
	v_mfma_f32_16x16x32_bf16 v[16:19], v[202:205], v[178:181], 0
	v_mfma_f32_16x16x32_bf16 v[4:7], v[194:197], v[186:189], 0
	v_mfma_f32_16x16x32_bf16 v[0:3], v[202:205], v[186:189], 0
	v_mfma_f32_16x16x32_bf16 v[52:55], v[198:201], v[148:151], v[52:55]
	v_mfma_f32_16x16x32_bf16 v[48:51], v[206:209], v[148:151], v[48:51]
	v_mfma_f32_16x16x32_bf16 v[36:39], v[198:201], v[174:177], v[36:39]
	v_mfma_f32_16x16x32_bf16 v[32:35], v[206:209], v[174:177], v[32:35]
	v_mfma_f32_16x16x32_bf16 v[20:23], v[198:201], v[182:185], v[20:23]
	v_mfma_f32_16x16x32_bf16 v[16:19], v[206:209], v[182:185], v[16:19]
	v_mfma_f32_16x16x32_bf16 v[4:7], v[198:201], v[190:193], v[4:7]
	s_setprio 0
	v_mfma_f32_16x16x32_bf16 v[0:3], v[206:209], v[190:193], v[0:3]
	s_barrier
	ds_read_b128 v[128:131], v140
	ds_read_b128 v[136:139], v140 offset:2048
	ds_read_b128 v[132:135], v140 offset:1024
	ds_read_b128 v[140:143], v140 offset:3072
	s_add_u32 s18, s18, 0x80000
	s_addc_u32 s19, s19, 0
	s_mov_b32 m0, s27
	v_lshl_add_u64 v[194:195], s[18:19], 0, v[156:157]
	ds_read_b128 v[144:147], v172 offset:32768
	ds_read_b128 v[166:169], v172 offset:34816
	ds_read_b128 v[178:181], v172 offset:36864
	ds_read_b128 v[186:189], v172 offset:38912
	ds_read_b128 v[148:151], v172 offset:33792
	ds_read_b128 v[174:177], v172 offset:35840
	ds_read_b128 v[182:185], v172 offset:37888
	ds_read_b128 v[190:193], v172 offset:39936
	global_load_lds_dwordx4 v[194:195], off
	s_mov_b32 m0, s28
	v_lshl_add_u64 v[194:195], s[18:19], 0, v[158:159]
	global_load_lds_dwordx4 v[194:195], off
	s_add_i32 s40, 0, 0x1c000
	s_add_u32 s18, s14, 0x4000
	s_addc_u32 s19, s15, 0
	s_add_i32 s39, s39, s23
	v_add_u32_e32 v152, s40, v170
	ds_read_b128 v[194:197], v152
	ds_read_b128 v[202:205], v152 offset:2048
	ds_read_b128 v[198:201], v152 offset:1024
	ds_read_b128 v[206:209], v152 offset:3072
	s_waitcnt lgkmcnt(0)
	s_barrier
	v_mfma_f32_16x16x32_bf16 v[124:127], v[128:131], v[144:147], v[124:127]
	s_setprio 1
	v_mfma_f32_16x16x32_bf16 v[120:123], v[136:139], v[144:147], v[120:123]
	v_mfma_f32_16x16x32_bf16 v[108:111], v[128:131], v[166:169], v[108:111]
	v_mfma_f32_16x16x32_bf16 v[104:107], v[136:139], v[166:169], v[104:107]
	v_mfma_f32_16x16x32_bf16 v[92:95], v[128:131], v[178:181], v[92:95]
	v_mfma_f32_16x16x32_bf16 v[88:91], v[136:139], v[178:181], v[88:91]
	v_mfma_f32_16x16x32_bf16 v[76:79], v[128:131], v[186:189], v[76:79]
	v_mfma_f32_16x16x32_bf16 v[72:75], v[136:139], v[186:189], v[72:75]
	v_mfma_f32_16x16x32_bf16 v[124:127], v[132:135], v[148:151], v[124:127]
	v_mfma_f32_16x16x32_bf16 v[120:123], v[140:143], v[148:151], v[120:123]
	v_mfma_f32_16x16x32_bf16 v[108:111], v[132:135], v[174:177], v[108:111]
	v_mfma_f32_16x16x32_bf16 v[104:107], v[140:143], v[174:177], v[104:107]
	v_mfma_f32_16x16x32_bf16 v[92:95], v[132:135], v[182:185], v[92:95]
	v_mfma_f32_16x16x32_bf16 v[88:91], v[140:143], v[182:185], v[88:91]
	v_mfma_f32_16x16x32_bf16 v[76:79], v[132:135], v[190:193], v[76:79]
	v_mfma_f32_16x16x32_bf16 v[72:75], v[140:143], v[190:193], v[72:75]
	v_mfma_f32_16x16x32_bf16 v[116:119], v[194:197], v[144:147], v[116:119]
	v_mfma_f32_16x16x32_bf16 v[112:115], v[202:205], v[144:147], v[112:115]
	v_mfma_f32_16x16x32_bf16 v[100:103], v[194:197], v[166:169], v[100:103]
	v_mfma_f32_16x16x32_bf16 v[96:99], v[202:205], v[166:169], v[96:99]
	v_mfma_f32_16x16x32_bf16 v[84:87], v[194:197], v[178:181], v[84:87]
	v_mfma_f32_16x16x32_bf16 v[80:83], v[202:205], v[178:181], v[80:83]
	v_mfma_f32_16x16x32_bf16 v[68:71], v[194:197], v[186:189], v[68:71]
	v_mfma_f32_16x16x32_bf16 v[64:67], v[202:205], v[186:189], v[64:67]
	v_mfma_f32_16x16x32_bf16 v[116:119], v[198:201], v[148:151], v[116:119]
	v_mfma_f32_16x16x32_bf16 v[112:115], v[206:209], v[148:151], v[112:115]
	v_mfma_f32_16x16x32_bf16 v[100:103], v[198:201], v[174:177], v[100:103]
	v_mfma_f32_16x16x32_bf16 v[96:99], v[206:209], v[174:177], v[96:99]
	v_mfma_f32_16x16x32_bf16 v[84:87], v[198:201], v[182:185], v[84:87]
	v_mfma_f32_16x16x32_bf16 v[80:83], v[206:209], v[182:185], v[80:83]
	v_mfma_f32_16x16x32_bf16 v[68:71], v[198:201], v[190:193], v[68:71]
	s_setprio 0
	v_mfma_f32_16x16x32_bf16 v[64:67], v[206:209], v[190:193], v[64:67]
	s_barrier
; #define PG8_STAGE(bufoff, gbase, voff) do { _Pragma("unroll") for (int _i = 0; _i < 2; ++_i) \
;         __builtin_amdgcn_global_load_lds((const unsigned*)((const char*)(gbase) + (voff)[_i]), (LAS unsigned*)(lds + (bufoff) + ldsw + _i * 8192), 16, 0, 0); } while (0)
; #define PG8_LDA(dst, b, h) do { _Pragma("unroll") for (int m = 0; m < 4; ++m) _Pragma("unroll") for (int k = 0; k < 2; ++k) dst[m][k] = *(const LAS bf16x8*)(lds + PG8_SA(b, h) + aoff + m * 2048 + k * 1024); } while (0)
; #define PG8_WAIT_V(n) asm volatile("s_waitcnt vmcnt(" #n ")" ::: "memory")
; #define PG8_WAIT_L(n) asm volatile("s_waitcnt lgkmcnt(" #n ")" ::: "memory")
; template <class Epi>
; __device__ __forceinline__ void gemm_phase(LAS unsigned char* lds, const Gemm g, const StaticOrder& S, const Epi& E) {
;     ...
;         for (int t = 0; t < nt; t += 2) {
;             const bool last = (t == nt - 2);
;             const char* a1 = cA + (size_t)(t + 1) * kstep;
;             const char* a2 = last ? nA : cA + (size_t)(t + 2) * kstep; const char* b2 = last ? nB : cB + (size_t)(t + 2) * kstep;
;             const char* a3 = a2 + kstep; const char* b3 = b2 + kstep;
;             PG8_LDB(B0, 0, 0); PG8_SCHED; PG8_LDA(At, 0, 0); PG8_STAGE(PG8_SA(1, 1), a1 + hstepA, voffA);
;             PG8_WAIT_L(8); PG8_BAR; PG8_WAIT_L(0); PG8_MMA(0, 0, At, B0); PG8_BAR; PG8_SCHED;
;             PG8_LDB(B1, 0, 1); PG8_STAGE(PG8_SB(0, 0), b2, voffB);
;             PG8_BAR; PG8_WAIT_L(0); PG8_MMA(0, 1, At, B1); PG8_BAR;
;             PG8_LDA(At, 0, 1); PG8_STAGE(PG8_SA(0, 0), a2, voffA);
;             PG8_BAR; PG8_WAIT_L(0); PG8_MMA(1, 0, At, B0); PG8_BAR; PG8_SCHED;
;             PG8_STAGE(PG8_SB(0, 1), b2 + hstepB, voffB);
;             PG8_WAIT_V(6); PG8_BAR; PG8_MMA(1, 1, At, B1); PG8_BAR;
;             PG8_LDB(B0, 1, 0); PG8_SCHED; PG8_LDA(At, 1, 0); PG8_STAGE(PG8_SA(0, 1), a2 + hstepA, voffA);
;             PG8_WAIT_L(8); PG8_BAR; PG8_WAIT_L(0); PG8_MMA(0, 0, At, B0); PG8_BAR; PG8_SCHED;
;             PG8_LDB(B1, 1, 1); PG8_STAGE(PG8_SB(1, 0), b3, voffB);
;             PG8_BAR; PG8_WAIT_L(0); PG8_MMA(0, 1, At, B1); PG8_BAR;
;             PG8_LDA(At, 1, 1); PG8_STAGE(PG8_SA(1, 0), a3, voffA);
;             PG8_BAR; PG8_WAIT_L(0); PG8_MMA(1, 0, At, B0); PG8_BAR; PG8_SCHED;
;             PG8_STAGE(PG8_SB(1, 1), b3 + hstepB, voffB);
;             PG8_WAIT_V(6); PG8_BAR; PG8_MMA(1, 1, At, B1); PG8_BAR;
	ds_read_b128 v[144:147], v172 offset:49152
	ds_read_b128 v[166:169], v172 offset:51200
	ds_read_b128 v[178:181], v172 offset:53248
	ds_read_b128 v[186:189], v172 offset:55296
	ds_read_b128 v[148:151], v172 offset:50176
	ds_read_b128 v[174:177], v172 offset:52224
	ds_read_b128 v[182:185], v172 offset:54272
	ds_read_b128 v[190:193], v172 offset:56320
	s_mov_b32 m0, s39
	v_lshl_add_u64 v[210:211], s[18:19], 0, v[156:157]
	global_load_lds_dwordx4 v[210:211], off
	s_add_i32 m0, s39, 0x2000
	v_lshl_add_u64 v[210:211], s[18:19], 0, v[158:159]
	global_load_lds_dwordx4 v[210:211], off
	s_mov_b32 m0, s29
	v_lshl_add_u64 v[210:211], s[16:17], 0, v[156:157]
	global_load_lds_dwordx4 v[210:211], off
	s_mov_b32 m0, s30
	v_lshl_add_u64 v[210:211], s[16:17], 0, v[158:159]
	global_load_lds_dwordx4 v[210:211], off
	s_add_u32 s14, s14, 0x84000
	s_addc_u32 s15, s15, 0
	s_add_i32 s16, s40, s23
	s_mov_b32 m0, s16
	v_lshl_add_u64 v[210:211], s[14:15], 0, v[156:157]
	global_load_lds_dwordx4 v[210:211], off
	s_add_i32 m0, s16, 0x2000
	v_lshl_add_u64 v[210:211], s[14:15], 0, v[158:159]
	global_load_lds_dwordx4 v[210:211], off
	s_waitcnt vmcnt(6)
	s_waitcnt lgkmcnt(0)
	s_barrier
	v_mfma_f32_16x16x32_bf16 v[60:63], v[128:131], v[144:147], v[60:63]
	s_setprio 1
	v_mfma_f32_16x16x32_bf16 v[56:59], v[136:139], v[144:147], v[56:59]
	v_mfma_f32_16x16x32_bf16 v[44:47], v[128:131], v[166:169], v[44:47]
	v_mfma_f32_16x16x32_bf16 v[40:43], v[136:139], v[166:169], v[40:43]
	v_mfma_f32_16x16x32_bf16 v[28:31], v[128:131], v[178:181], v[28:31]
	v_mfma_f32_16x16x32_bf16 v[24:27], v[136:139], v[178:181], v[24:27]
	v_mfma_f32_16x16x32_bf16 v[12:15], v[128:131], v[186:189], v[12:15]
	v_mfma_f32_16x16x32_bf16 v[8:11], v[136:139], v[186:189], v[8:11]
	v_mfma_f32_16x16x32_bf16 v[60:63], v[132:135], v[148:151], v[60:63]
	v_mfma_f32_16x16x32_bf16 v[56:59], v[140:143], v[148:151], v[56:59]
	v_mfma_f32_16x16x32_bf16 v[44:47], v[132:135], v[174:177], v[44:47]
	v_mfma_f32_16x16x32_bf16 v[40:43], v[140:143], v[174:177], v[40:43]
	v_mfma_f32_16x16x32_bf16 v[28:31], v[132:135], v[182:185], v[28:31]
	v_mfma_f32_16x16x32_bf16 v[24:27], v[140:143], v[182:185], v[24:27]
	v_mfma_f32_16x16x32_bf16 v[12:15], v[132:135], v[190:193], v[12:15]
	v_mfma_f32_16x16x32_bf16 v[8:11], v[140:143], v[190:193], v[8:11]
	v_mfma_f32_16x16x32_bf16 v[52:55], v[194:197], v[144:147], v[52:55]
	v_mfma_f32_16x16x32_bf16 v[48:51], v[202:205], v[144:147], v[48:51]
	s_add_i32 s38, s38, 2
	s_add_u32 s12, s12, 0x8000
	s_addc_u32 s13, s13, 0
	s_add_u32 s36, s36, 0x8000
	s_addc_u32 s37, s37, 0
	v_mfma_f32_16x16x32_bf16 v[36:39], v[194:197], v[166:169], v[36:39]
	v_mfma_f32_16x16x32_bf16 v[32:35], v[202:205], v[166:169], v[32:35]
	v_mfma_f32_16x16x32_bf16 v[20:23], v[194:197], v[178:181], v[20:23]
	v_mfma_f32_16x16x32_bf16 v[16:19], v[202:205], v[178:181], v[16:19]
	v_mfma_f32_16x16x32_bf16 v[4:7], v[194:197], v[186:189], v[4:7]
	v_mfma_f32_16x16x32_bf16 v[0:3], v[202:205], v[186:189], v[0:3]
	v_mfma_f32_16x16x32_bf16 v[52:55], v[198:201], v[148:151], v[52:55]
	v_mfma_f32_16x16x32_bf16 v[48:51], v[206:209], v[148:151], v[48:51]
	v_mfma_f32_16x16x32_bf16 v[36:39], v[198:201], v[174:177], v[36:39]
	v_mfma_f32_16x16x32_bf16 v[32:35], v[206:209], v[174:177], v[32:35]
	v_mfma_f32_16x16x32_bf16 v[20:23], v[198:201], v[182:185], v[20:23]
	v_mfma_f32_16x16x32_bf16 v[16:19], v[206:209], v[182:185], v[16:19]
	v_mfma_f32_16x16x32_bf16 v[4:7], v[198:201], v[190:193], v[4:7]
	s_cmp_gt_u32 s38, 29
	s_setprio 0
	v_mfma_f32_16x16x32_bf16 v[0:3], v[206:209], v[190:193], v[0:3]
	s_barrier
	s_cbranch_scc0 .LBB0_247
	s_branch .Lpeel_done_247
.LBB0_247:
	s_add_u32 s14, s12, 0xfff84000
	s_addc_u32 s15, s13, -1
	s_cmp_eq_u32 s38, 28
	s_cselect_b32 s18, s11, s14
	s_cselect_b32 s19, s5, s15
	s_cselect_b32 s14, s35, s36
	s_cselect_b32 s15, s3, s37
	s_add_u32 s16, s18, 0x4000
	s_addc_u32 s17, s19, 0
	s_add_i32 s39, 0, 0x10000
	v_add_u32_e32 v140, s39, v170
	ds_read_b128 v[128:131], v140
	ds_read_b128 v[136:139], v140 offset:2048
	ds_read_b128 v[132:135], v140 offset:1024
	ds_read_b128 v[140:143], v140 offset:3072
	v_lshl_add_u64 v[194:195], s[12:13], 0, v[156:157]
	s_add_i32 m0, s25, 0xc000
	ds_read_b128 v[144:147], v172
	ds_read_b128 v[166:169], v172 offset:2048
	ds_read_b128 v[178:181], v172 offset:4096
	ds_read_b128 v[186:189], v172 offset:6144
	ds_read_b128 v[148:151], v172 offset:1024
	ds_read_b128 v[174:177], v172 offset:3072
	ds_read_b128 v[182:185], v172 offset:5120
	ds_read_b128 v[190:193], v172 offset:7168
	global_load_lds_dwordx4 v[194:195], off
	s_add_i32 m0, s25, 0xe000
	v_lshl_add_u64 v[194:195], s[12:13], 0, v[158:159]
	global_load_lds_dwordx4 v[194:195], off
	s_add_i32 s42, 0, 0x14000
	s_add_i32 s39, s39, s23
	v_add_u32_e32 v152, s42, v170
	ds_read_b128 v[194:197], v152
	ds_read_b128 v[202:205], v152 offset:2048
	ds_read_b128 v[198:201], v152 offset:1024
	ds_read_b128 v[206:209], v152 offset:3072
	s_waitcnt lgkmcnt(0)
	s_barrier
; #define PG8_STAGE(bufoff, gbase, voff) do { _Pragma("unroll") for (int _i = 0; _i < 2; ++_i) \
;         __builtin_amdgcn_global_load_lds((const unsigned*)((const char*)(gbase) + (voff)[_i]), (LAS unsigned*)(lds + (bufoff) + ldsw + _i * 8192), 16, 0, 0); } while (0)
; #define PG8_LDA(dst, b, h) do { _Pragma("unroll") for (int m = 0; m < 4; ++m) _Pragma("unroll") for (int k = 0; k < 2; ++k) dst[m][k] = *(const LAS bf16x8*)(lds + PG8_SA(b, h) + aoff + m * 2048 + k * 1024); } while (0)
; #define PG8_LDB(dst, b, h) do { _Pragma("unroll") for (int n = 0; n < 2; ++n) _Pragma("unroll") for (int k = 0; k < 2; ++k) dst[n][k] = *(const LAS bf16x8*)(lds + PG8_SB(b, h) + boff + n * 2048 + k * 1024); } while (0)
; #define PG8_MMA(ai, bj, At, Bt) do { __builtin_amdgcn_s_setprio(1); _Pragma("unroll") for (int m = 0; m < 4; ++m) _Pragma("unroll") for (int n = 0; n < 2; ++n) _Pragma("unroll") for (int k = 0; k < 2; ++k) \
;         acc[ai][bj][m][n] = __builtin_amdgcn_mfma_f32_16x16x32_bf16(Bt[n][k], At[m][k], acc[ai][bj][m][n], 0, 0, 0); __builtin_amdgcn_s_setprio(0); } while (0)
; #define PG8_WAIT_V(n) asm volatile("s_waitcnt vmcnt(" #n ")" ::: "memory")
; #define PG8_WAIT_L(n) asm volatile("s_waitcnt lgkmcnt(" #n ")" ::: "memory")
; #define PG8_BAR __builtin_amdgcn_s_barrier()
; #define PG8_SCHED __builtin_amdgcn_sched_barrier(0)
; template <class Epi>
; __device__ __forceinline__ void gemm_phase(LAS unsigned char* lds, const Gemm g, const StaticOrder& S, const Epi& E) {
;     ...
;             PG8_WAIT_L(8); PG8_BAR; PG8_WAIT_L(0); PG8_MMA(0, 0, At, B0); PG8_BAR; PG8_SCHED;
;             PG8_LDB(B1, 0, 1); PG8_STAGE(PG8_SB(0, 0), b2, voffB);
;             PG8_BAR; PG8_WAIT_L(0); PG8_MMA(0, 1, At, B1); PG8_BAR;
;             PG8_LDA(At, 0, 1); PG8_STAGE(PG8_SA(0, 0), a2, voffA);
;             PG8_BAR; PG8_WAIT_L(0); PG8_MMA(1, 0, At, B0); PG8_BAR; PG8_SCHED;
;             PG8_STAGE(PG8_SB(0, 1), b2 + hstepB, voffB);
;             PG8_WAIT_V(6); PG8_BAR; PG8_MMA(1, 1, At, B1); PG8_BAR;
;             PG8_LDB(B0, 1, 0); PG8_SCHED; PG8_LDA(At, 1, 0); PG8_STAGE(PG8_SA(0, 1), a2 + hstepA, voffA);
;             PG8_WAIT_L(8); PG8_BAR; PG8_WAIT_L(0); PG8_MMA(0, 0, At, B0); PG8_BAR; PG8_SCHED;
	v_mfma_f32_16x16x32_bf16 v[124:127], v[128:131], v[144:147], v[124:127]
	s_setprio 1
	v_mfma_f32_16x16x32_bf16 v[120:123], v[136:139], v[144:147], v[120:123]
	v_mfma_f32_16x16x32_bf16 v[108:111], v[128:131], v[166:169], v[108:111]
	v_mfma_f32_16x16x32_bf16 v[104:107], v[136:139], v[166:169], v[104:107]
	v_mfma_f32_16x16x32_bf16 v[92:95], v[128:131], v[178:181], v[92:95]
	v_mfma_f32_16x16x32_bf16 v[88:91], v[136:139], v[178:181], v[88:91]
	v_mfma_f32_16x16x32_bf16 v[76:79], v[128:131], v[186:189], v[76:79]
	v_mfma_f32_16x16x32_bf16 v[72:75], v[136:139], v[186:189], v[72:75]
	v_mfma_f32_16x16x32_bf16 v[124:127], v[132:135], v[148:151], v[124:127]
	v_mfma_f32_16x16x32_bf16 v[120:123], v[140:143], v[148:151], v[120:123]
	v_mfma_f32_16x16x32_bf16 v[108:111], v[132:135], v[174:177], v[108:111]
	v_mfma_f32_16x16x32_bf16 v[104:107], v[140:143], v[174:177], v[104:107]
	v_mfma_f32_16x16x32_bf16 v[92:95], v[132:135], v[182:185], v[92:95]
	v_mfma_f32_16x16x32_bf16 v[88:91], v[140:143], v[182:185], v[88:91]
	v_mfma_f32_16x16x32_bf16 v[76:79], v[132:135], v[190:193], v[76:79]
	v_mfma_f32_16x16x32_bf16 v[72:75], v[140:143], v[190:193], v[72:75]
	v_mfma_f32_16x16x32_bf16 v[116:119], v[194:197], v[144:147], v[116:119]
	v_mfma_f32_16x16x32_bf16 v[112:115], v[202:205], v[144:147], v[112:115]
	v_mfma_f32_16x16x32_bf16 v[100:103], v[194:197], v[166:169], v[100:103]
	v_mfma_f32_16x16x32_bf16 v[96:99], v[202:205], v[166:169], v[96:99]
	v_mfma_f32_16x16x32_bf16 v[84:87], v[194:197], v[178:181], v[84:87]
	v_mfma_f32_16x16x32_bf16 v[80:83], v[202:205], v[178:181], v[80:83]
	v_mfma_f32_16x16x32_bf16 v[68:71], v[194:197], v[186:189], v[68:71]
	v_mfma_f32_16x16x32_bf16 v[64:67], v[202:205], v[186:189], v[64:67]
	v_mfma_f32_16x16x32_bf16 v[116:119], v[198:201], v[148:151], v[116:119]
	v_mfma_f32_16x16x32_bf16 v[112:115], v[206:209], v[148:151], v[112:115]
	v_mfma_f32_16x16x32_bf16 v[100:103], v[198:201], v[174:177], v[100:103]
	v_mfma_f32_16x16x32_bf16 v[96:99], v[206:209], v[174:177], v[96:99]
	v_mfma_f32_16x16x32_bf16 v[84:87], v[198:201], v[182:185], v[84:87]
	v_mfma_f32_16x16x32_bf16 v[80:83], v[206:209], v[182:185], v[80:83]
	v_mfma_f32_16x16x32_bf16 v[68:71], v[198:201], v[190:193], v[68:71]
	s_setprio 0
	v_mfma_f32_16x16x32_bf16 v[64:67], v[206:209], v[190:193], v[64:67]
	s_barrier
	ds_read_b128 v[144:147], v172 offset:16384
	ds_read_b128 v[166:169], v172 offset:18432
	ds_read_b128 v[178:181], v172 offset:20480
	ds_read_b128 v[186:189], v172 offset:22528
	ds_read_b128 v[148:151], v172 offset:17408
	ds_read_b128 v[174:177], v172 offset:19456
	ds_read_b128 v[182:185], v172 offset:21504
	ds_read_b128 v[190:193], v172 offset:23552
	s_mov_b32 m0, s39
	v_lshl_add_u64 v[210:211], s[14:15], 0, v[156:157]
	global_load_lds_dwordx4 v[210:211], off
	s_add_i32 m0, s39, 0x2000
	v_lshl_add_u64 v[210:211], s[14:15], 0, v[158:159]
	global_load_lds_dwordx4 v[210:211], off
	s_mov_b32 m0, s25
	v_lshl_add_u64 v[210:211], s[18:19], 0, v[156:157]
	global_load_lds_dwordx4 v[210:211], off
	s_mov_b32 m0, s26
	v_lshl_add_u64 v[210:211], s[18:19], 0, v[158:159]
	global_load_lds_dwordx4 v[210:211], off
	s_add_u32 s40, s14, 0x80000
	s_addc_u32 s41, s15, 0
	s_add_i32 s39, s42, s23
	s_mov_b32 m0, s39
	v_lshl_add_u64 v[210:211], s[40:41], 0, v[156:157]
	global_load_lds_dwordx4 v[210:211], off
	s_add_i32 m0, s39, 0x2000
	v_lshl_add_u64 v[210:211], s[40:41], 0, v[158:159]
	global_load_lds_dwordx4 v[210:211], off
	s_waitcnt vmcnt(6)
	s_waitcnt lgkmcnt(0)
	s_barrier
	v_mfma_f32_16x16x32_bf16 v[60:63], v[128:131], v[144:147], v[60:63]
	s_setprio 1
	v_mfma_f32_16x16x32_bf16 v[56:59], v[136:139], v[144:147], v[56:59]
	v_mfma_f32_16x16x32_bf16 v[44:47], v[128:131], v[166:169], v[44:47]
	v_mfma_f32_16x16x32_bf16 v[40:43], v[136:139], v[166:169], v[40:43]
	v_mfma_f32_16x16x32_bf16 v[28:31], v[128:131], v[178:181], v[28:31]
	v_mfma_f32_16x16x32_bf16 v[24:27], v[136:139], v[178:181], v[24:27]
	v_mfma_f32_16x16x32_bf16 v[12:15], v[128:131], v[186:189], v[12:15]
	v_mfma_f32_16x16x32_bf16 v[8:11], v[136:139], v[186:189], v[8:11]
	v_mfma_f32_16x16x32_bf16 v[60:63], v[132:135], v[148:151], v[60:63]
	v_mfma_f32_16x16x32_bf16 v[56:59], v[140:143], v[148:151], v[56:59]
	v_mfma_f32_16x16x32_bf16 v[44:47], v[132:135], v[174:177], v[44:47]
	v_mfma_f32_16x16x32_bf16 v[40:43], v[140:143], v[174:177], v[40:43]
	v_mfma_f32_16x16x32_bf16 v[28:31], v[132:135], v[182:185], v[28:31]
	v_mfma_f32_16x16x32_bf16 v[24:27], v[140:143], v[182:185], v[24:27]
	v_mfma_f32_16x16x32_bf16 v[12:15], v[132:135], v[190:193], v[12:15]
	v_mfma_f32_16x16x32_bf16 v[8:11], v[140:143], v[190:193], v[8:11]
	v_mfma_f32_16x16x32_bf16 v[52:55], v[194:197], v[144:147], v[52:55]
	v_mfma_f32_16x16x32_bf16 v[48:51], v[202:205], v[144:147], v[48:51]
	s_add_i32 s39, 0, 0x18000
	v_add_u32_e32 v140, s39, v170
	v_mfma_f32_16x16x32_bf16 v[36:39], v[194:197], v[166:169], v[36:39]
	v_mfma_f32_16x16x32_bf16 v[32:35], v[202:205], v[166:169], v[32:35]
	v_mfma_f32_16x16x32_bf16 v[20:23], v[194:197], v[178:181], v[20:23]
	v_mfma_f32_16x16x32_bf16 v[16:19], v[202:205], v[178:181], v[16:19]
	v_mfma_f32_16x16x32_bf16 v[4:7], v[194:197], v[186:189], v[4:7]
	v_mfma_f32_16x16x32_bf16 v[0:3], v[202:205], v[186:189], v[0:3]
	v_mfma_f32_16x16x32_bf16 v[52:55], v[198:201], v[148:151], v[52:55]
	v_mfma_f32_16x16x32_bf16 v[48:51], v[206:209], v[148:151], v[48:51]
	v_mfma_f32_16x16x32_bf16 v[36:39], v[198:201], v[174:177], v[36:39]
	v_mfma_f32_16x16x32_bf16 v[32:35], v[206:209], v[174:177], v[32:35]
	v_mfma_f32_16x16x32_bf16 v[20:23], v[198:201], v[182:185], v[20:23]
	v_mfma_f32_16x16x32_bf16 v[16:19], v[206:209], v[182:185], v[16:19]
	v_mfma_f32_16x16x32_bf16 v[4:7], v[198:201], v[190:193], v[4:7]
	s_setprio 0
	v_mfma_f32_16x16x32_bf16 v[0:3], v[206:209], v[190:193], v[0:3]
	s_barrier
; #define PG8_STAGE(bufoff, gbase, voff) do { _Pragma("unroll") for (int _i = 0; _i < 2; ++_i) \
;         __builtin_amdgcn_global_load_lds((const unsigned*)((const char*)(gbase) + (voff)[_i]), (LAS unsigned*)(lds + (bufoff) + ldsw + _i * 8192), 16, 0, 0); } while (0)
; #define PG8_LDA(dst, b, h) do { _Pragma("unroll") for (int m = 0; m < 4; ++m) _Pragma("unroll") for (int k = 0; k < 2; ++k) dst[m][k] = *(const LAS bf16x8*)(lds + PG8_SA(b, h) + aoff + m * 2048 + k * 1024); } while (0)
; #define PG8_LDB(dst, b, h) do { _Pragma("unroll") for (int n = 0; n < 2; ++n) _Pragma("unroll") for (int k = 0; k < 2; ++k) dst[n][k] = *(const LAS bf16x8*)(lds + PG8_SB(b, h) + boff + n * 2048 + k * 1024); } while (0)
; #define PG8_MMA(ai, bj, At, Bt) do { __builtin_amdgcn_s_setprio(1); _Pragma("unroll") for (int m = 0; m < 4; ++m) _Pragma("unroll") for (int n = 0; n < 2; ++n) _Pragma("unroll") for (int k = 0; k < 2; ++k) \
;         acc[ai][bj][m][n] = __builtin_amdgcn_mfma_f32_16x16x32_bf16(Bt[n][k], At[m][k], acc[ai][bj][m][n], 0, 0, 0); __builtin_amdgcn_s_setprio(0); } while (0)
; #define PG8_WAIT_V(n) asm volatile("s_waitcnt vmcnt(" #n ")" ::: "memory")
; #define PG8_WAIT_L(n) asm volatile("s_waitcnt lgkmcnt(" #n ")" ::: "memory")
; #define PG8_BAR __builtin_amdgcn_s_barrier()
; #define PG8_SCHED __builtin_amdgcn_sched_barrier(0)
; template <class Epi>
; __device__ __forceinline__ void gemm_phase(LAS unsigned char* lds, const Gemm g, const StaticOrder& S, const Epi& E) {
;     ...
;             PG8_LDB(B0, 1, 0); PG8_SCHED; PG8_LDA(At, 1, 0); PG8_STAGE(PG8_SA(0, 1), a2 + hstepA, voffA);
;             PG8_WAIT_L(8); PG8_BAR; PG8_WAIT_L(0); PG8_MMA(0, 0, At, B0); PG8_BAR; PG8_SCHED;
;             PG8_LDB(B1, 1, 1); PG8_STAGE(PG8_SB(1, 0), b3, voffB);
;             PG8_BAR; PG8_WAIT_L(0); PG8_MMA(0, 1, At, B1); PG8_BAR;
;             PG8_LDA(At, 1, 1); PG8_STAGE(PG8_SA(1, 0), a3, voffA);
;             PG8_BAR; PG8_WAIT_L(0); PG8_MMA(1, 0, At, B0); PG8_BAR; PG8_SCHED;
;             PG8_STAGE(PG8_SB(1, 1), b3 + hstepB, voffB);
;             PG8_WAIT_V(6); PG8_BAR; PG8_MMA(1, 1, At, B1); PG8_BAR;
	ds_read_b128 v[128:131], v140
	ds_read_b128 v[136:139], v140 offset:2048
	ds_read_b128 v[132:135], v140 offset:1024
	ds_read_b128 v[140:143], v140 offset:3072
	s_add_u32 s18, s18, 0x80000
	s_addc_u32 s19, s19, 0
	s_mov_b32 m0, s27
	v_lshl_add_u64 v[194:195], s[18:19], 0, v[156:157]
	ds_read_b128 v[144:147], v172 offset:32768
	ds_read_b128 v[166:169], v172 offset:34816
	ds_read_b128 v[178:181], v172 offset:36864
	ds_read_b128 v[186:189], v172 offset:38912
	ds_read_b128 v[148:151], v172 offset:33792
	ds_read_b128 v[174:177], v172 offset:35840
	ds_read_b128 v[182:185], v172 offset:37888
	ds_read_b128 v[190:193], v172 offset:39936
	global_load_lds_dwordx4 v[194:195], off
	s_mov_b32 m0, s28
	v_lshl_add_u64 v[194:195], s[18:19], 0, v[158:159]
	global_load_lds_dwordx4 v[194:195], off
	s_add_i32 s40, 0, 0x1c000
	s_add_u32 s18, s14, 0x4000
	s_addc_u32 s19, s15, 0
	s_add_i32 s39, s39, s23
	v_add_u32_e32 v152, s40, v170
	ds_read_b128 v[194:197], v152
	ds_read_b128 v[202:205], v152 offset:2048
	ds_read_b128 v[198:201], v152 offset:1024
	ds_read_b128 v[206:209], v152 offset:3072
	s_waitcnt lgkmcnt(0)
	s_barrier
	v_mfma_f32_16x16x32_bf16 v[124:127], v[128:131], v[144:147], v[124:127]
	s_setprio 1
	v_mfma_f32_16x16x32_bf16 v[120:123], v[136:139], v[144:147], v[120:123]
	v_mfma_f32_16x16x32_bf16 v[108:111], v[128:131], v[166:169], v[108:111]
	v_mfma_f32_16x16x32_bf16 v[104:107], v[136:139], v[166:169], v[104:107]
	v_mfma_f32_16x16x32_bf16 v[92:95], v[128:131], v[178:181], v[92:95]
	v_mfma_f32_16x16x32_bf16 v[88:91], v[136:139], v[178:181], v[88:91]
	v_mfma_f32_16x16x32_bf16 v[76:79], v[128:131], v[186:189], v[76:79]
	v_mfma_f32_16x16x32_bf16 v[72:75], v[136:139], v[186:189], v[72:75]
	v_mfma_f32_16x16x32_bf16 v[124:127], v[132:135], v[148:151], v[124:127]
	v_mfma_f32_16x16x32_bf16 v[120:123], v[140:143], v[148:151], v[120:123]
	v_mfma_f32_16x16x32_bf16 v[108:111], v[132:135], v[174:177], v[108:111]
	v_mfma_f32_16x16x32_bf16 v[104:107], v[140:143], v[174:177], v[104:107]
	v_mfma_f32_16x16x32_bf16 v[92:95], v[132:135], v[182:185], v[92:95]
	v_mfma_f32_16x16x32_bf16 v[88:91], v[140:143], v[182:185], v[88:91]
	v_mfma_f32_16x16x32_bf16 v[76:79], v[132:135], v[190:193], v[76:79]
	v_mfma_f32_16x16x32_bf16 v[72:75], v[140:143], v[190:193], v[72:75]
	v_mfma_f32_16x16x32_bf16 v[116:119], v[194:197], v[144:147], v[116:119]
	v_mfma_f32_16x16x32_bf16 v[112:115], v[202:205], v[144:147], v[112:115]
	v_mfma_f32_16x16x32_bf16 v[100:103], v[194:197], v[166:169], v[100:103]
	v_mfma_f32_16x16x32_bf16 v[96:99], v[202:205], v[166:169], v[96:99]
	v_mfma_f32_16x16x32_bf16 v[84:87], v[194:197], v[178:181], v[84:87]
	v_mfma_f32_16x16x32_bf16 v[80:83], v[202:205], v[178:181], v[80:83]
	v_mfma_f32_16x16x32_bf16 v[68:71], v[194:197], v[186:189], v[68:71]
	v_mfma_f32_16x16x32_bf16 v[64:67], v[202:205], v[186:189], v[64:67]
	v_mfma_f32_16x16x32_bf16 v[116:119], v[198:201], v[148:151], v[116:119]
	v_mfma_f32_16x16x32_bf16 v[112:115], v[206:209], v[148:151], v[112:115]
	v_mfma_f32_16x16x32_bf16 v[100:103], v[198:201], v[174:177], v[100:103]
	v_mfma_f32_16x16x32_bf16 v[96:99], v[206:209], v[174:177], v[96:99]
	v_mfma_f32_16x16x32_bf16 v[84:87], v[198:201], v[182:185], v[84:87]
	v_mfma_f32_16x16x32_bf16 v[80:83], v[206:209], v[182:185], v[80:83]
	v_mfma_f32_16x16x32_bf16 v[68:71], v[198:201], v[190:193], v[68:71]
	s_setprio 0
	v_mfma_f32_16x16x32_bf16 v[64:67], v[206:209], v[190:193], v[64:67]
	s_barrier
	ds_read_b128 v[144:147], v172 offset:49152
	ds_read_b128 v[166:169], v172 offset:51200
	ds_read_b128 v[178:181], v172 offset:53248
	ds_read_b128 v[186:189], v172 offset:55296
	ds_read_b128 v[148:151], v172 offset:50176
	ds_read_b128 v[174:177], v172 offset:52224
	ds_read_b128 v[182:185], v172 offset:54272
	ds_read_b128 v[190:193], v172 offset:56320
	s_mov_b32 m0, s39
	v_lshl_add_u64 v[210:211], s[18:19], 0, v[156:157]
	global_load_lds_dwordx4 v[210:211], off
	s_add_i32 m0, s39, 0x2000
	v_lshl_add_u64 v[210:211], s[18:19], 0, v[158:159]
	global_load_lds_dwordx4 v[210:211], off
	s_mov_b32 m0, s29
	v_lshl_add_u64 v[210:211], s[16:17], 0, v[156:157]
	global_load_lds_dwordx4 v[210:211], off
	s_mov_b32 m0, s30
	v_lshl_add_u64 v[210:211], s[16:17], 0, v[158:159]
	global_load_lds_dwordx4 v[210:211], off
	s_add_u32 s14, s14, 0x84000
	s_addc_u32 s15, s15, 0
	s_add_i32 s16, s40, s23
	s_mov_b32 m0, s16
	v_lshl_add_u64 v[210:211], s[14:15], 0, v[156:157]
	global_load_lds_dwordx4 v[210:211], off
	s_add_i32 m0, s16, 0x2000
	v_lshl_add_u64 v[210:211], s[14:15], 0, v[158:159]
	global_load_lds_dwordx4 v[210:211], off
	s_waitcnt vmcnt(6)
	s_waitcnt lgkmcnt(0)
	s_barrier
	v_mfma_f32_16x16x32_bf16 v[60:63], v[128:131], v[144:147], v[60:63]
	s_setprio 1
	v_mfma_f32_16x16x32_bf16 v[56:59], v[136:139], v[144:147], v[56:59]
	v_mfma_f32_16x16x32_bf16 v[44:47], v[128:131], v[166:169], v[44:47]
	v_mfma_f32_16x16x32_bf16 v[40:43], v[136:139], v[166:169], v[40:43]
	v_mfma_f32_16x16x32_bf16 v[28:31], v[128:131], v[178:181], v[28:31]
	v_mfma_f32_16x16x32_bf16 v[24:27], v[136:139], v[178:181], v[24:27]
	v_mfma_f32_16x16x32_bf16 v[12:15], v[128:131], v[186:189], v[12:15]
	v_mfma_f32_16x16x32_bf16 v[8:11], v[136:139], v[186:189], v[8:11]
	v_mfma_f32_16x16x32_bf16 v[60:63], v[132:135], v[148:151], v[60:63]
	v_mfma_f32_16x16x32_bf16 v[56:59], v[140:143], v[148:151], v[56:59]
	v_mfma_f32_16x16x32_bf16 v[44:47], v[132:135], v[174:177], v[44:47]
	v_mfma_f32_16x16x32_bf16 v[40:43], v[140:143], v[174:177], v[40:43]
	v_mfma_f32_16x16x32_bf16 v[28:31], v[132:135], v[182:185], v[28:31]
	v_mfma_f32_16x16x32_bf16 v[24:27], v[140:143], v[182:185], v[24:27]
	v_mfma_f32_16x16x32_bf16 v[12:15], v[132:135], v[190:193], v[12:15]
	v_mfma_f32_16x16x32_bf16 v[8:11], v[140:143], v[190:193], v[8:11]
	v_mfma_f32_16x16x32_bf16 v[52:55], v[194:197], v[144:147], v[52:55]
	v_mfma_f32_16x16x32_bf16 v[48:51], v[202:205], v[144:147], v[48:51]
	s_add_i32 s38, s38, 2
	s_add_u32 s12, s12, 0x8000
	s_addc_u32 s13, s13, 0
	s_add_u32 s36, s36, 0x8000
	s_addc_u32 s37, s37, 0
	v_mfma_f32_16x16x32_bf16 v[36:39], v[194:197], v[166:169], v[36:39]
	v_mfma_f32_16x16x32_bf16 v[32:35], v[202:205], v[166:169], v[32:35]
	v_mfma_f32_16x16x32_bf16 v[20:23], v[194:197], v[178:181], v[20:23]
	v_mfma_f32_16x16x32_bf16 v[16:19], v[202:205], v[178:181], v[16:19]
	v_mfma_f32_16x16x32_bf16 v[4:7], v[194:197], v[186:189], v[4:7]
	v_mfma_f32_16x16x32_bf16 v[0:3], v[202:205], v[186:189], v[0:3]
	v_mfma_f32_16x16x32_bf16 v[52:55], v[198:201], v[148:151], v[52:55]
	v_mfma_f32_16x16x32_bf16 v[48:51], v[206:209], v[148:151], v[48:51]
	v_mfma_f32_16x16x32_bf16 v[36:39], v[198:201], v[174:177], v[36:39]
	v_mfma_f32_16x16x32_bf16 v[32:35], v[206:209], v[174:177], v[32:35]
	v_mfma_f32_16x16x32_bf16 v[20:23], v[198:201], v[182:185], v[20:23]
	v_mfma_f32_16x16x32_bf16 v[16:19], v[206:209], v[182:185], v[16:19]
	v_mfma_f32_16x16x32_bf16 v[4:7], v[198:201], v[190:193], v[4:7]
	s_cmp_gt_u32 s38, 29
	s_setprio 0
	v_mfma_f32_16x16x32_bf16 v[0:3], v[206:209], v[190:193], v[0:3]
	s_barrier
	s_cbranch_scc0 .LBB0_247
